# scan waves write per-lane y partials again; staging sums them with bank-conflict-free rotated ds_read_b128 order
# speedup vs baseline: 1.0263x; 1.0263x over previous
.LBB0_649:
	s_and_b64 vcc, exec, s[0:1]
	s_cbranch_vccz .LBB0_676
	s_cmpk_lt_u32 s3, 0x100
	s_mov_b64 s[0:1], -1
	s_cbranch_scc0 .LBB0_654
	v_lshrrev_b32_e32 v1, 4, v152
	v_lshl_or_b32 v1, s50, 2, v1
	v_and_b32_e32 v118, 15, v153
	v_lshlrev_b32_e32 v6, 4, v118
	v_mov_b32_e32 v7, 0
	v_lshlrev_b32_e32 v8, 2, v1
	v_add_u32_e32 v8, 0x9300, v8
	v_add_u32_e32 v120, 0x400, v8
	v_lshlrev_b32_e32 v9, 6, v1
	v_lshl_add_u32 v9, v118, 2, v9
	v_add_u32_e32 v9, 0x9b00, v9
	v_mov_b32_e32 v2, 0
	v_mov_b32_e32 v3, 0
	v_mov_b32_e32 v4, 0
	v_mov_b32_e32 v5, 0
	s_mov_b32 s0, 0
	s_mov_b32 s1, 0x11b00
	s_waitcnt vmcnt(0) lgkmcnt(0)
	s_barrier
.LBB0_652:
	ds_read_b128 v[20:23], v6 offset:0
	ds_read_b128 v[28:31], v6 offset:512
	ds_read_b128 v[24:27], v6 offset:256
	ds_read_b128 v[32:35], v6 offset:768
	ds_read_b128 v[56:59], v7 offset:36864
	ds_read_b128 v[36:39], v6 offset:1024
	ds_read_b128 v[40:43], v6 offset:1280
	ds_read2_b32 v[64:65], v8 offset0:0 offset1:16
	ds_read_b128 v[48:51], v6 offset:1792
	ds_read_b128 v[44:47], v6 offset:1536
	ds_read_b128 v[52:55], v6 offset:2048
	ds_read_b128 v[60:63], v7 offset:36880
	s_waitcnt lgkmcnt(7)
	v_pk_mul_f32 v[10:11], v[4:5], v[22:23]
	ds_read_b128 v[68:71], v6 offset:2304
	v_pk_mul_f32 v[12:13], v[4:5], v[30:31]
	v_pk_fma_f32 v[10:11], v[2:3], v[20:21], v[10:11]
	v_pk_fma_f32 v[12:13], v[2:3], v[28:29], v[12:13]
	ds_read_b128 v[76:79], v6 offset:2816
	v_pk_mul_f32 v[14:15], v[4:5], v[26:27]
	v_add_f32_e32 v10, v10, v11
	v_add_f32_e32 v12, v12, v13
	ds_read_b128 v[72:75], v6 offset:2560
	v_pk_mul_f32 v[16:17], v[4:5], v[34:35]
	v_fma_f32 v12, -v56, v10, v12
	v_add_f32_dpp v10, v10, v10 row_ror:8 row_mask:0xf bank_mask:0xf bound_ctrl:1
	ds_read_b128 v[80:83], v6 offset:3072
	v_pk_fma_f32 v[14:15], v[2:3], v[24:25], v[14:15]
	v_add_f32_dpp v12, v12, v12 row_ror:8 row_mask:0xf bank_mask:0xf bound_ctrl:1
	v_add_f32_dpp v10, v10, v10 row_ror:4 row_mask:0xf bank_mask:0xf bound_ctrl:1
	ds_read_b128 v[104:107], v7 offset:36912
	v_pk_fma_f32 v[16:17], v[2:3], v[32:33], v[16:17]
	v_add_f32_dpp v12, v12, v12 row_ror:4 row_mask:0xf bank_mask:0xf bound_ctrl:1
	v_add_f32_dpp v10, v10, v10 row_ror:2 row_mask:0xf bank_mask:0xf bound_ctrl:1
	ds_read_b128 v[84:87], v6 offset:3328
	s_waitcnt lgkmcnt(10)
	v_pk_mul_f32 v[114:115], v[2:3], v[36:37]
	v_add_f32_dpp v12, v12, v12 row_ror:2 row_mask:0xf bank_mask:0xf bound_ctrl:1
	v_add_f32_dpp v10, v10, v10 row_ror:1 row_mask:0xf bank_mask:0xf bound_ctrl:1
	ds_read_b128 v[88:91], v6 offset:3584
	v_pk_mul_f32 v[116:117], v[4:5], v[38:39]
	v_add_f32_dpp v12, v12, v12 row_ror:1 row_mask:0xf bank_mask:0xf bound_ctrl:1
	v_add_f32_e32 v14, v14, v15
	ds_read2_b32 v[112:113], v8 offset0:32 offset1:48
	v_pk_fma_f32 v[114:115], v[40:41], v[64:65], v[114:115] op_sel_hi:[1,0,1]
	v_add_f32_e32 v16, v16, v17
	v_pk_fma_f32 v[116:117], v[42:43], v[64:65], v[116:117] op_sel_hi:[1,0,1]
	ds_read_b128 v[96:99], v6 offset:4096
	v_fmac_f32_e32 v12, v64, v57
	v_fmac_f32_e32 v14, v64, v59
	s_waitcnt lgkmcnt(9)
	v_pk_fma_f32 v[114:115], v[48:49], v[64:65], v[114:115] op_sel:[0,1,0] op_sel_hi:[1,1,1]
	ds_read_b128 v[92:95], v6 offset:3840
	v_fmac_f32_e32 v16, v64, v61
	v_pk_fma_f32 v[116:117], v[50:51], v[64:65], v[116:117] op_sel:[0,1,0] op_sel_hi:[1,1,1]
	v_fma_f32 v14, -v10, v58, v14
	ds_read_b128 v[100:103], v6 offset:4352
	v_fmac_f32_e32 v16, v65, v63
	v_pk_fma_f32 v[114:115], v[44:45], v[10:11], v[114:115] op_sel_hi:[1,0,1] neg_lo:[1,0,0] neg_hi:[1,0,0]
	v_fma_f32 v16, -v10, v60, v16
	ds_read_b128 v[108:111], v7 offset:36928
	v_pk_fma_f32 v[116:117], v[46:47], v[10:11], v[116:117] op_sel_hi:[1,0,1] neg_lo:[1,0,0] neg_hi:[1,0,0]
	v_fma_f32 v16, -v12, v62, v16
	v_pk_fma_f32 v[2:3], v[52:53], v[12:13], v[114:115] op_sel_hi:[1,0,1] neg_lo:[1,0,0] neg_hi:[1,0,0]
	v_pk_fma_f32 v[4:5], v[54:55], v[12:13], v[116:117] op_sel_hi:[1,0,1] neg_lo:[1,0,0] neg_hi:[1,0,0]
	ds_write2st64_b32 v9, v14, v16 offset0:0 offset1:4
	s_waitcnt lgkmcnt(8)
	v_pk_mul_f32 v[10:11], v[4:5], v[70:71]
	ds_read_b128 v[20:23], v6 offset:4608
	v_pk_mul_f32 v[12:13], v[4:5], v[78:79]
	v_pk_fma_f32 v[10:11], v[2:3], v[68:69], v[10:11]
	v_pk_fma_f32 v[12:13], v[2:3], v[76:77], v[12:13]
	ds_read_b128 v[28:31], v6 offset:5120
	v_pk_mul_f32 v[14:15], v[4:5], v[74:75]
	v_add_f32_e32 v10, v10, v11
	v_add_f32_e32 v12, v12, v13
	ds_read_b128 v[24:27], v6 offset:4864
	v_pk_mul_f32 v[16:17], v[4:5], v[82:83]
	v_fma_f32 v12, -v104, v10, v12
	v_add_f32_dpp v10, v10, v10 row_ror:8 row_mask:0xf bank_mask:0xf bound_ctrl:1
	ds_read_b128 v[32:35], v6 offset:5376
	v_pk_fma_f32 v[14:15], v[2:3], v[72:73], v[14:15]
	v_add_f32_dpp v12, v12, v12 row_ror:8 row_mask:0xf bank_mask:0xf bound_ctrl:1
	v_add_f32_dpp v10, v10, v10 row_ror:4 row_mask:0xf bank_mask:0xf bound_ctrl:1
	ds_read_b128 v[56:59], v7 offset:36960
	v_pk_fma_f32 v[16:17], v[2:3], v[80:81], v[16:17]
	v_add_f32_dpp v12, v12, v12 row_ror:4 row_mask:0xf bank_mask:0xf bound_ctrl:1
	v_add_f32_dpp v10, v10, v10 row_ror:2 row_mask:0xf bank_mask:0xf bound_ctrl:1
	ds_read_b128 v[36:39], v6 offset:5632
	s_waitcnt lgkmcnt(11)
	v_pk_mul_f32 v[114:115], v[2:3], v[84:85]
	v_add_f32_dpp v12, v12, v12 row_ror:2 row_mask:0xf bank_mask:0xf bound_ctrl:1
	v_add_f32_dpp v10, v10, v10 row_ror:1 row_mask:0xf bank_mask:0xf bound_ctrl:1
	ds_read_b128 v[40:43], v6 offset:5888
	v_pk_mul_f32 v[116:117], v[4:5], v[86:87]
	v_add_f32_dpp v12, v12, v12 row_ror:1 row_mask:0xf bank_mask:0xf bound_ctrl:1
	v_add_f32_e32 v14, v14, v15
	ds_read2_b32 v[64:65], v8 offset0:64 offset1:80
	v_pk_fma_f32 v[114:115], v[88:89], v[112:113], v[114:115] op_sel_hi:[1,0,1]
	v_add_f32_e32 v16, v16, v17
	v_pk_fma_f32 v[116:117], v[90:91], v[112:113], v[116:117] op_sel_hi:[1,0,1]
	ds_read_b128 v[48:51], v6 offset:6400
	v_fmac_f32_e32 v12, v112, v105
	v_fmac_f32_e32 v14, v112, v107
	s_waitcnt lgkmcnt(10)
	v_pk_fma_f32 v[114:115], v[96:97], v[112:113], v[114:115] op_sel:[0,1,0] op_sel_hi:[1,1,1]
	ds_read_b128 v[44:47], v6 offset:6144
	v_fmac_f32_e32 v16, v112, v109
	v_pk_fma_f32 v[116:117], v[98:99], v[112:113], v[116:117] op_sel:[0,1,0] op_sel_hi:[1,1,1]
	v_fma_f32 v14, -v10, v106, v14
	ds_read_b128 v[52:55], v6 offset:6656
	v_fmac_f32_e32 v16, v113, v111
	v_pk_fma_f32 v[114:115], v[92:93], v[10:11], v[114:115] op_sel_hi:[1,0,1] neg_lo:[1,0,0] neg_hi:[1,0,0]
	v_fma_f32 v16, -v10, v108, v16
	ds_read_b128 v[60:63], v7 offset:36976
	v_pk_fma_f32 v[116:117], v[94:95], v[10:11], v[116:117] op_sel_hi:[1,0,1] neg_lo:[1,0,0] neg_hi:[1,0,0]
	v_fma_f32 v16, -v12, v110, v16
	v_pk_fma_f32 v[2:3], v[100:101], v[12:13], v[114:115] op_sel_hi:[1,0,1] neg_lo:[1,0,0] neg_hi:[1,0,0]
	v_pk_fma_f32 v[4:5], v[102:103], v[12:13], v[116:117] op_sel_hi:[1,0,1] neg_lo:[1,0,0] neg_hi:[1,0,0]
	ds_write2st64_b32 v9, v14, v16 offset0:8 offset1:12
	s_waitcnt lgkmcnt(8)
	v_pk_mul_f32 v[10:11], v[4:5], v[22:23]
	ds_read_b128 v[68:71], v6 offset:6912
	v_pk_mul_f32 v[12:13], v[4:5], v[30:31]
	v_pk_fma_f32 v[10:11], v[2:3], v[20:21], v[10:11]
	v_pk_fma_f32 v[12:13], v[2:3], v[28:29], v[12:13]
	ds_read_b128 v[76:79], v6 offset:7424
	v_pk_mul_f32 v[14:15], v[4:5], v[26:27]
	v_add_f32_e32 v10, v10, v11
	v_add_f32_e32 v12, v12, v13
	ds_read_b128 v[72:75], v6 offset:7168
	v_pk_mul_f32 v[16:17], v[4:5], v[34:35]
	v_fma_f32 v12, -v56, v10, v12
	v_add_f32_dpp v10, v10, v10 row_ror:8 row_mask:0xf bank_mask:0xf bound_ctrl:1
	ds_read_b128 v[80:83], v6 offset:7680
	v_pk_fma_f32 v[14:15], v[2:3], v[24:25], v[14:15]
	v_add_f32_dpp v12, v12, v12 row_ror:8 row_mask:0xf bank_mask:0xf bound_ctrl:1
	v_add_f32_dpp v10, v10, v10 row_ror:4 row_mask:0xf bank_mask:0xf bound_ctrl:1
	ds_read_b128 v[104:107], v7 offset:37008
	v_pk_fma_f32 v[16:17], v[2:3], v[32:33], v[16:17]
	v_add_f32_dpp v12, v12, v12 row_ror:4 row_mask:0xf bank_mask:0xf bound_ctrl:1
	v_add_f32_dpp v10, v10, v10 row_ror:2 row_mask:0xf bank_mask:0xf bound_ctrl:1
	ds_read_b128 v[84:87], v6 offset:7936
	s_waitcnt lgkmcnt(11)
	v_pk_mul_f32 v[114:115], v[2:3], v[36:37]
	v_add_f32_dpp v12, v12, v12 row_ror:2 row_mask:0xf bank_mask:0xf bound_ctrl:1
	v_add_f32_dpp v10, v10, v10 row_ror:1 row_mask:0xf bank_mask:0xf bound_ctrl:1
	ds_read_b128 v[88:91], v6 offset:8192
	v_pk_mul_f32 v[116:117], v[4:5], v[38:39]
	v_add_f32_dpp v12, v12, v12 row_ror:1 row_mask:0xf bank_mask:0xf bound_ctrl:1
	v_add_f32_e32 v14, v14, v15
	ds_read2_b32 v[112:113], v8 offset0:96 offset1:112
	v_pk_fma_f32 v[114:115], v[40:41], v[64:65], v[114:115] op_sel_hi:[1,0,1]
	v_add_f32_e32 v16, v16, v17
	v_pk_fma_f32 v[116:117], v[42:43], v[64:65], v[116:117] op_sel_hi:[1,0,1]
	ds_read_b128 v[96:99], v6 offset:8704
	v_fmac_f32_e32 v12, v64, v57
	v_fmac_f32_e32 v14, v64, v59
	s_waitcnt lgkmcnt(10)
	v_pk_fma_f32 v[114:115], v[48:49], v[64:65], v[114:115] op_sel:[0,1,0] op_sel_hi:[1,1,1]
	ds_read_b128 v[92:95], v6 offset:8448
	v_fmac_f32_e32 v16, v64, v61
	v_pk_fma_f32 v[116:117], v[50:51], v[64:65], v[116:117] op_sel:[0,1,0] op_sel_hi:[1,1,1]
	v_fma_f32 v14, -v10, v58, v14
	ds_read_b128 v[100:103], v6 offset:8960
	v_fmac_f32_e32 v16, v65, v63
	v_pk_fma_f32 v[114:115], v[44:45], v[10:11], v[114:115] op_sel_hi:[1,0,1] neg_lo:[1,0,0] neg_hi:[1,0,0]
	v_fma_f32 v16, -v10, v60, v16
	ds_read_b128 v[108:111], v7 offset:37024
	v_pk_fma_f32 v[116:117], v[46:47], v[10:11], v[116:117] op_sel_hi:[1,0,1] neg_lo:[1,0,0] neg_hi:[1,0,0]
	v_fma_f32 v16, -v12, v62, v16
	v_pk_fma_f32 v[2:3], v[52:53], v[12:13], v[114:115] op_sel_hi:[1,0,1] neg_lo:[1,0,0] neg_hi:[1,0,0]
	v_pk_fma_f32 v[4:5], v[54:55], v[12:13], v[116:117] op_sel_hi:[1,0,1] neg_lo:[1,0,0] neg_hi:[1,0,0]
	ds_write2st64_b32 v9, v14, v16 offset0:16 offset1:20
	s_waitcnt lgkmcnt(8)
	v_pk_mul_f32 v[10:11], v[4:5], v[70:71]
	ds_read_b128 v[20:23], v6 offset:9216
	v_pk_mul_f32 v[12:13], v[4:5], v[78:79]
	v_pk_fma_f32 v[10:11], v[2:3], v[68:69], v[10:11]
	v_pk_fma_f32 v[12:13], v[2:3], v[76:77], v[12:13]
	ds_read_b128 v[28:31], v6 offset:9728
	v_pk_mul_f32 v[14:15], v[4:5], v[74:75]
	v_add_f32_e32 v10, v10, v11
	v_add_f32_e32 v12, v12, v13
	ds_read_b128 v[24:27], v6 offset:9472
	v_pk_mul_f32 v[16:17], v[4:5], v[82:83]
	v_fma_f32 v12, -v104, v10, v12
	v_add_f32_dpp v10, v10, v10 row_ror:8 row_mask:0xf bank_mask:0xf bound_ctrl:1
	ds_read_b128 v[32:35], v6 offset:9984
	v_pk_fma_f32 v[14:15], v[2:3], v[72:73], v[14:15]
	v_add_f32_dpp v12, v12, v12 row_ror:8 row_mask:0xf bank_mask:0xf bound_ctrl:1
	v_add_f32_dpp v10, v10, v10 row_ror:4 row_mask:0xf bank_mask:0xf bound_ctrl:1
	ds_read_b128 v[56:59], v7 offset:37056
	v_pk_fma_f32 v[16:17], v[2:3], v[80:81], v[16:17]
	v_add_f32_dpp v12, v12, v12 row_ror:4 row_mask:0xf bank_mask:0xf bound_ctrl:1
	v_add_f32_dpp v10, v10, v10 row_ror:2 row_mask:0xf bank_mask:0xf bound_ctrl:1
	ds_read_b128 v[36:39], v6 offset:10240
	s_waitcnt lgkmcnt(11)
	v_pk_mul_f32 v[114:115], v[2:3], v[84:85]
	v_add_f32_dpp v12, v12, v12 row_ror:2 row_mask:0xf bank_mask:0xf bound_ctrl:1
	v_add_f32_dpp v10, v10, v10 row_ror:1 row_mask:0xf bank_mask:0xf bound_ctrl:1
	ds_read_b128 v[40:43], v6 offset:10496
	v_pk_mul_f32 v[116:117], v[4:5], v[86:87]
	v_add_f32_dpp v12, v12, v12 row_ror:1 row_mask:0xf bank_mask:0xf bound_ctrl:1
	v_add_f32_e32 v14, v14, v15
	ds_read2_b32 v[64:65], v8 offset0:128 offset1:144
	v_pk_fma_f32 v[114:115], v[88:89], v[112:113], v[114:115] op_sel_hi:[1,0,1]
	v_add_f32_e32 v16, v16, v17
	v_pk_fma_f32 v[116:117], v[90:91], v[112:113], v[116:117] op_sel_hi:[1,0,1]
	ds_read_b128 v[48:51], v6 offset:11008
	v_fmac_f32_e32 v12, v112, v105
	v_fmac_f32_e32 v14, v112, v107
	s_waitcnt lgkmcnt(10)
	v_pk_fma_f32 v[114:115], v[96:97], v[112:113], v[114:115] op_sel:[0,1,0] op_sel_hi:[1,1,1]
	ds_read_b128 v[44:47], v6 offset:10752
	v_fmac_f32_e32 v16, v112, v109
	v_pk_fma_f32 v[116:117], v[98:99], v[112:113], v[116:117] op_sel:[0,1,0] op_sel_hi:[1,1,1]
	v_fma_f32 v14, -v10, v106, v14
	ds_read_b128 v[52:55], v6 offset:11264
	v_fmac_f32_e32 v16, v113, v111
	v_pk_fma_f32 v[114:115], v[92:93], v[10:11], v[114:115] op_sel_hi:[1,0,1] neg_lo:[1,0,0] neg_hi:[1,0,0]
	v_fma_f32 v16, -v10, v108, v16
	ds_read_b128 v[60:63], v7 offset:37072
	v_pk_fma_f32 v[116:117], v[94:95], v[10:11], v[116:117] op_sel_hi:[1,0,1] neg_lo:[1,0,0] neg_hi:[1,0,0]
	v_fma_f32 v16, -v12, v110, v16
	v_pk_fma_f32 v[2:3], v[100:101], v[12:13], v[114:115] op_sel_hi:[1,0,1] neg_lo:[1,0,0] neg_hi:[1,0,0]
	v_pk_fma_f32 v[4:5], v[102:103], v[12:13], v[116:117] op_sel_hi:[1,0,1] neg_lo:[1,0,0] neg_hi:[1,0,0]
	ds_write2st64_b32 v9, v14, v16 offset0:24 offset1:28
	s_waitcnt lgkmcnt(8)
	v_pk_mul_f32 v[10:11], v[4:5], v[22:23]
	ds_read_b128 v[68:71], v6 offset:11520
	v_pk_mul_f32 v[12:13], v[4:5], v[30:31]
	v_pk_fma_f32 v[10:11], v[2:3], v[20:21], v[10:11]
	v_pk_fma_f32 v[12:13], v[2:3], v[28:29], v[12:13]
	ds_read_b128 v[76:79], v6 offset:12032
	v_pk_mul_f32 v[14:15], v[4:5], v[26:27]
	v_add_f32_e32 v10, v10, v11
	v_add_f32_e32 v12, v12, v13
	ds_read_b128 v[72:75], v6 offset:11776
	v_pk_mul_f32 v[16:17], v[4:5], v[34:35]
	v_fma_f32 v12, -v56, v10, v12
	v_add_f32_dpp v10, v10, v10 row_ror:8 row_mask:0xf bank_mask:0xf bound_ctrl:1
	ds_read_b128 v[80:83], v6 offset:12288
	v_pk_fma_f32 v[14:15], v[2:3], v[24:25], v[14:15]
	v_add_f32_dpp v12, v12, v12 row_ror:8 row_mask:0xf bank_mask:0xf bound_ctrl:1
	v_add_f32_dpp v10, v10, v10 row_ror:4 row_mask:0xf bank_mask:0xf bound_ctrl:1
	ds_read_b128 v[104:107], v7 offset:37104
	v_pk_fma_f32 v[16:17], v[2:3], v[32:33], v[16:17]
	v_add_f32_dpp v12, v12, v12 row_ror:4 row_mask:0xf bank_mask:0xf bound_ctrl:1
	v_add_f32_dpp v10, v10, v10 row_ror:2 row_mask:0xf bank_mask:0xf bound_ctrl:1
	ds_read_b128 v[84:87], v6 offset:12544
	s_waitcnt lgkmcnt(11)
	v_pk_mul_f32 v[114:115], v[2:3], v[36:37]
	v_add_f32_dpp v12, v12, v12 row_ror:2 row_mask:0xf bank_mask:0xf bound_ctrl:1
	v_add_f32_dpp v10, v10, v10 row_ror:1 row_mask:0xf bank_mask:0xf bound_ctrl:1
	ds_read_b128 v[88:91], v6 offset:12800
	v_pk_mul_f32 v[116:117], v[4:5], v[38:39]
	v_add_f32_dpp v12, v12, v12 row_ror:1 row_mask:0xf bank_mask:0xf bound_ctrl:1
	v_add_f32_e32 v14, v14, v15
	ds_read2_b32 v[112:113], v8 offset0:160 offset1:176
	v_pk_fma_f32 v[114:115], v[40:41], v[64:65], v[114:115] op_sel_hi:[1,0,1]
	v_add_f32_e32 v16, v16, v17
	v_pk_fma_f32 v[116:117], v[42:43], v[64:65], v[116:117] op_sel_hi:[1,0,1]
	ds_read_b128 v[96:99], v6 offset:13312
	v_fmac_f32_e32 v12, v64, v57
	v_fmac_f32_e32 v14, v64, v59
	s_waitcnt lgkmcnt(10)
	v_pk_fma_f32 v[114:115], v[48:49], v[64:65], v[114:115] op_sel:[0,1,0] op_sel_hi:[1,1,1]
	ds_read_b128 v[92:95], v6 offset:13056
	v_fmac_f32_e32 v16, v64, v61
	v_pk_fma_f32 v[116:117], v[50:51], v[64:65], v[116:117] op_sel:[0,1,0] op_sel_hi:[1,1,1]
	v_fma_f32 v14, -v10, v58, v14
	ds_read_b128 v[100:103], v6 offset:13568
	v_fmac_f32_e32 v16, v65, v63
	v_pk_fma_f32 v[114:115], v[44:45], v[10:11], v[114:115] op_sel_hi:[1,0,1] neg_lo:[1,0,0] neg_hi:[1,0,0]
	v_fma_f32 v16, -v10, v60, v16
	ds_read_b128 v[108:111], v7 offset:37120
	v_pk_fma_f32 v[116:117], v[46:47], v[10:11], v[116:117] op_sel_hi:[1,0,1] neg_lo:[1,0,0] neg_hi:[1,0,0]
	v_fma_f32 v16, -v12, v62, v16
	v_pk_fma_f32 v[2:3], v[52:53], v[12:13], v[114:115] op_sel_hi:[1,0,1] neg_lo:[1,0,0] neg_hi:[1,0,0]
	v_pk_fma_f32 v[4:5], v[54:55], v[12:13], v[116:117] op_sel_hi:[1,0,1] neg_lo:[1,0,0] neg_hi:[1,0,0]
	ds_write2st64_b32 v9, v14, v16 offset0:32 offset1:36
	s_waitcnt lgkmcnt(8)
	v_pk_mul_f32 v[10:11], v[4:5], v[70:71]
	ds_read_b128 v[20:23], v6 offset:13824
	v_pk_mul_f32 v[12:13], v[4:5], v[78:79]
	v_pk_fma_f32 v[10:11], v[2:3], v[68:69], v[10:11]
	v_pk_fma_f32 v[12:13], v[2:3], v[76:77], v[12:13]
	ds_read_b128 v[28:31], v6 offset:14336
	v_pk_mul_f32 v[14:15], v[4:5], v[74:75]
	v_add_f32_e32 v10, v10, v11
	v_add_f32_e32 v12, v12, v13
	ds_read_b128 v[24:27], v6 offset:14080
	v_pk_mul_f32 v[16:17], v[4:5], v[82:83]
	v_fma_f32 v12, -v104, v10, v12
	v_add_f32_dpp v10, v10, v10 row_ror:8 row_mask:0xf bank_mask:0xf bound_ctrl:1
	ds_read_b128 v[32:35], v6 offset:14592
	v_pk_fma_f32 v[14:15], v[2:3], v[72:73], v[14:15]
	v_add_f32_dpp v12, v12, v12 row_ror:8 row_mask:0xf bank_mask:0xf bound_ctrl:1
	v_add_f32_dpp v10, v10, v10 row_ror:4 row_mask:0xf bank_mask:0xf bound_ctrl:1
	ds_read_b128 v[56:59], v7 offset:37152
	v_pk_fma_f32 v[16:17], v[2:3], v[80:81], v[16:17]
	v_add_f32_dpp v12, v12, v12 row_ror:4 row_mask:0xf bank_mask:0xf bound_ctrl:1
	v_add_f32_dpp v10, v10, v10 row_ror:2 row_mask:0xf bank_mask:0xf bound_ctrl:1
	ds_read_b128 v[36:39], v6 offset:14848
	s_waitcnt lgkmcnt(11)
	v_pk_mul_f32 v[114:115], v[2:3], v[84:85]
	v_add_f32_dpp v12, v12, v12 row_ror:2 row_mask:0xf bank_mask:0xf bound_ctrl:1
	v_add_f32_dpp v10, v10, v10 row_ror:1 row_mask:0xf bank_mask:0xf bound_ctrl:1
	ds_read_b128 v[40:43], v6 offset:15104
	v_pk_mul_f32 v[116:117], v[4:5], v[86:87]
	v_add_f32_dpp v12, v12, v12 row_ror:1 row_mask:0xf bank_mask:0xf bound_ctrl:1
	v_add_f32_e32 v14, v14, v15
	ds_read2_b32 v[64:65], v8 offset0:192 offset1:208
	v_pk_fma_f32 v[114:115], v[88:89], v[112:113], v[114:115] op_sel_hi:[1,0,1]
	v_add_f32_e32 v16, v16, v17
	v_pk_fma_f32 v[116:117], v[90:91], v[112:113], v[116:117] op_sel_hi:[1,0,1]
	ds_read_b128 v[48:51], v6 offset:15616
	v_fmac_f32_e32 v12, v112, v105
	v_fmac_f32_e32 v14, v112, v107
	s_waitcnt lgkmcnt(10)
	v_pk_fma_f32 v[114:115], v[96:97], v[112:113], v[114:115] op_sel:[0,1,0] op_sel_hi:[1,1,1]
	ds_read_b128 v[44:47], v6 offset:15360
	v_fmac_f32_e32 v16, v112, v109
	v_pk_fma_f32 v[116:117], v[98:99], v[112:113], v[116:117] op_sel:[0,1,0] op_sel_hi:[1,1,1]
	v_fma_f32 v14, -v10, v106, v14
	ds_read_b128 v[52:55], v6 offset:15872
	v_fmac_f32_e32 v16, v113, v111
	v_pk_fma_f32 v[114:115], v[92:93], v[10:11], v[114:115] op_sel_hi:[1,0,1] neg_lo:[1,0,0] neg_hi:[1,0,0]
	v_fma_f32 v16, -v10, v108, v16
	ds_read_b128 v[60:63], v7 offset:37168
	v_pk_fma_f32 v[116:117], v[94:95], v[10:11], v[116:117] op_sel_hi:[1,0,1] neg_lo:[1,0,0] neg_hi:[1,0,0]
	v_fma_f32 v16, -v12, v110, v16
	v_pk_fma_f32 v[2:3], v[100:101], v[12:13], v[114:115] op_sel_hi:[1,0,1] neg_lo:[1,0,0] neg_hi:[1,0,0]
	v_pk_fma_f32 v[4:5], v[102:103], v[12:13], v[116:117] op_sel_hi:[1,0,1] neg_lo:[1,0,0] neg_hi:[1,0,0]
	ds_write2st64_b32 v9, v14, v16 offset0:40 offset1:44
	s_waitcnt lgkmcnt(8)
	v_pk_mul_f32 v[10:11], v[4:5], v[22:23]
	ds_read_b128 v[68:71], v6 offset:16128
	v_pk_mul_f32 v[12:13], v[4:5], v[30:31]
	v_pk_fma_f32 v[10:11], v[2:3], v[20:21], v[10:11]
	v_pk_fma_f32 v[12:13], v[2:3], v[28:29], v[12:13]
	ds_read_b128 v[76:79], v6 offset:16640
	v_pk_mul_f32 v[14:15], v[4:5], v[26:27]
	v_add_f32_e32 v10, v10, v11
	v_add_f32_e32 v12, v12, v13
	ds_read_b128 v[72:75], v6 offset:16384
	v_pk_mul_f32 v[16:17], v[4:5], v[34:35]
	v_fma_f32 v12, -v56, v10, v12
	v_add_f32_dpp v10, v10, v10 row_ror:8 row_mask:0xf bank_mask:0xf bound_ctrl:1
	ds_read_b128 v[80:83], v6 offset:16896
	v_pk_fma_f32 v[14:15], v[2:3], v[24:25], v[14:15]
	v_add_f32_dpp v12, v12, v12 row_ror:8 row_mask:0xf bank_mask:0xf bound_ctrl:1
	v_add_f32_dpp v10, v10, v10 row_ror:4 row_mask:0xf bank_mask:0xf bound_ctrl:1
	ds_read_b128 v[104:107], v7 offset:37200
	v_pk_fma_f32 v[16:17], v[2:3], v[32:33], v[16:17]
	v_add_f32_dpp v12, v12, v12 row_ror:4 row_mask:0xf bank_mask:0xf bound_ctrl:1
	v_add_f32_dpp v10, v10, v10 row_ror:2 row_mask:0xf bank_mask:0xf bound_ctrl:1
	ds_read_b128 v[84:87], v6 offset:17152
	s_waitcnt lgkmcnt(11)
	v_pk_mul_f32 v[114:115], v[2:3], v[36:37]
	v_add_f32_dpp v12, v12, v12 row_ror:2 row_mask:0xf bank_mask:0xf bound_ctrl:1
	v_add_f32_dpp v10, v10, v10 row_ror:1 row_mask:0xf bank_mask:0xf bound_ctrl:1
	ds_read_b128 v[88:91], v6 offset:17408
	v_pk_mul_f32 v[116:117], v[4:5], v[38:39]
	v_add_f32_dpp v12, v12, v12 row_ror:1 row_mask:0xf bank_mask:0xf bound_ctrl:1
	v_add_f32_e32 v14, v14, v15
	ds_read2_b32 v[112:113], v8 offset0:224 offset1:240
	v_pk_fma_f32 v[114:115], v[40:41], v[64:65], v[114:115] op_sel_hi:[1,0,1]
	v_add_f32_e32 v16, v16, v17
	v_pk_fma_f32 v[116:117], v[42:43], v[64:65], v[116:117] op_sel_hi:[1,0,1]
	ds_read_b128 v[96:99], v6 offset:17920
	v_fmac_f32_e32 v12, v64, v57
	v_fmac_f32_e32 v14, v64, v59
	s_waitcnt lgkmcnt(10)
	v_pk_fma_f32 v[114:115], v[48:49], v[64:65], v[114:115] op_sel:[0,1,0] op_sel_hi:[1,1,1]
	ds_read_b128 v[92:95], v6 offset:17664
	v_fmac_f32_e32 v16, v64, v61
	v_pk_fma_f32 v[116:117], v[50:51], v[64:65], v[116:117] op_sel:[0,1,0] op_sel_hi:[1,1,1]
	v_fma_f32 v14, -v10, v58, v14
	ds_read_b128 v[100:103], v6 offset:18176
	v_fmac_f32_e32 v16, v65, v63
	v_pk_fma_f32 v[114:115], v[44:45], v[10:11], v[114:115] op_sel_hi:[1,0,1] neg_lo:[1,0,0] neg_hi:[1,0,0]
	v_fma_f32 v16, -v10, v60, v16
	ds_read_b128 v[108:111], v7 offset:37216
	v_pk_fma_f32 v[116:117], v[46:47], v[10:11], v[116:117] op_sel_hi:[1,0,1] neg_lo:[1,0,0] neg_hi:[1,0,0]
	v_fma_f32 v16, -v12, v62, v16
	v_pk_fma_f32 v[2:3], v[52:53], v[12:13], v[114:115] op_sel_hi:[1,0,1] neg_lo:[1,0,0] neg_hi:[1,0,0]
	v_pk_fma_f32 v[4:5], v[54:55], v[12:13], v[116:117] op_sel_hi:[1,0,1] neg_lo:[1,0,0] neg_hi:[1,0,0]
	ds_write2st64_b32 v9, v14, v16 offset0:48 offset1:52
	s_waitcnt lgkmcnt(8)
	v_pk_mul_f32 v[10:11], v[4:5], v[70:71]
	ds_read_b128 v[20:23], v6 offset:18432
	v_pk_mul_f32 v[12:13], v[4:5], v[78:79]
	v_pk_fma_f32 v[10:11], v[2:3], v[68:69], v[10:11]
	v_pk_fma_f32 v[12:13], v[2:3], v[76:77], v[12:13]
	ds_read_b128 v[28:31], v6 offset:18944
	v_pk_mul_f32 v[14:15], v[4:5], v[74:75]
	v_add_f32_e32 v10, v10, v11
	v_add_f32_e32 v12, v12, v13
	ds_read_b128 v[24:27], v6 offset:18688
	v_pk_mul_f32 v[16:17], v[4:5], v[82:83]
	v_fma_f32 v12, -v104, v10, v12
	v_add_f32_dpp v10, v10, v10 row_ror:8 row_mask:0xf bank_mask:0xf bound_ctrl:1
	ds_read_b128 v[32:35], v6 offset:19200
	v_pk_fma_f32 v[14:15], v[2:3], v[72:73], v[14:15]
	v_add_f32_dpp v12, v12, v12 row_ror:8 row_mask:0xf bank_mask:0xf bound_ctrl:1
	v_add_f32_dpp v10, v10, v10 row_ror:4 row_mask:0xf bank_mask:0xf bound_ctrl:1
	ds_read_b128 v[56:59], v7 offset:37248
	v_pk_fma_f32 v[16:17], v[2:3], v[80:81], v[16:17]
	v_add_f32_dpp v12, v12, v12 row_ror:4 row_mask:0xf bank_mask:0xf bound_ctrl:1
	v_add_f32_dpp v10, v10, v10 row_ror:2 row_mask:0xf bank_mask:0xf bound_ctrl:1
	ds_read_b128 v[36:39], v6 offset:19456
	s_waitcnt lgkmcnt(11)
	v_pk_mul_f32 v[114:115], v[2:3], v[84:85]
	v_add_f32_dpp v12, v12, v12 row_ror:2 row_mask:0xf bank_mask:0xf bound_ctrl:1
	v_add_f32_dpp v10, v10, v10 row_ror:1 row_mask:0xf bank_mask:0xf bound_ctrl:1
	ds_read_b128 v[40:43], v6 offset:19712
	v_pk_mul_f32 v[116:117], v[4:5], v[86:87]
	v_add_f32_dpp v12, v12, v12 row_ror:1 row_mask:0xf bank_mask:0xf bound_ctrl:1
	v_add_f32_e32 v14, v14, v15
	ds_read2_b32 v[64:65], v120 offset0:0 offset1:16
	v_pk_fma_f32 v[114:115], v[88:89], v[112:113], v[114:115] op_sel_hi:[1,0,1]
	v_add_f32_e32 v16, v16, v17
	v_pk_fma_f32 v[116:117], v[90:91], v[112:113], v[116:117] op_sel_hi:[1,0,1]
	ds_read_b128 v[48:51], v6 offset:20224
	v_fmac_f32_e32 v12, v112, v105
	v_fmac_f32_e32 v14, v112, v107
	s_waitcnt lgkmcnt(10)
	v_pk_fma_f32 v[114:115], v[96:97], v[112:113], v[114:115] op_sel:[0,1,0] op_sel_hi:[1,1,1]
	ds_read_b128 v[44:47], v6 offset:19968
	v_fmac_f32_e32 v16, v112, v109
	v_pk_fma_f32 v[116:117], v[98:99], v[112:113], v[116:117] op_sel:[0,1,0] op_sel_hi:[1,1,1]
	v_fma_f32 v14, -v10, v106, v14
	ds_read_b128 v[52:55], v6 offset:20480
	v_fmac_f32_e32 v16, v113, v111
	v_pk_fma_f32 v[114:115], v[92:93], v[10:11], v[114:115] op_sel_hi:[1,0,1] neg_lo:[1,0,0] neg_hi:[1,0,0]
	v_fma_f32 v16, -v10, v108, v16
	ds_read_b128 v[60:63], v7 offset:37264
	v_pk_fma_f32 v[116:117], v[94:95], v[10:11], v[116:117] op_sel_hi:[1,0,1] neg_lo:[1,0,0] neg_hi:[1,0,0]
	v_fma_f32 v16, -v12, v110, v16
	v_pk_fma_f32 v[2:3], v[100:101], v[12:13], v[114:115] op_sel_hi:[1,0,1] neg_lo:[1,0,0] neg_hi:[1,0,0]
	v_pk_fma_f32 v[4:5], v[102:103], v[12:13], v[116:117] op_sel_hi:[1,0,1] neg_lo:[1,0,0] neg_hi:[1,0,0]
	ds_write2st64_b32 v9, v14, v16 offset0:56 offset1:60
	s_waitcnt lgkmcnt(8)
	v_pk_mul_f32 v[10:11], v[4:5], v[22:23]
	ds_read_b128 v[68:71], v6 offset:20736
	v_pk_mul_f32 v[12:13], v[4:5], v[30:31]
	v_pk_fma_f32 v[10:11], v[2:3], v[20:21], v[10:11]
	v_pk_fma_f32 v[12:13], v[2:3], v[28:29], v[12:13]
	ds_read_b128 v[76:79], v6 offset:21248
	v_pk_mul_f32 v[14:15], v[4:5], v[26:27]
	v_add_f32_e32 v10, v10, v11
	v_add_f32_e32 v12, v12, v13
	ds_read_b128 v[72:75], v6 offset:20992
	v_pk_mul_f32 v[16:17], v[4:5], v[34:35]
	v_fma_f32 v12, -v56, v10, v12
	v_add_f32_dpp v10, v10, v10 row_ror:8 row_mask:0xf bank_mask:0xf bound_ctrl:1
	ds_read_b128 v[80:83], v6 offset:21504
	v_pk_fma_f32 v[14:15], v[2:3], v[24:25], v[14:15]
	v_add_f32_dpp v12, v12, v12 row_ror:8 row_mask:0xf bank_mask:0xf bound_ctrl:1
	v_add_f32_dpp v10, v10, v10 row_ror:4 row_mask:0xf bank_mask:0xf bound_ctrl:1
	ds_read_b128 v[104:107], v7 offset:37296
	v_pk_fma_f32 v[16:17], v[2:3], v[32:33], v[16:17]
	v_add_f32_dpp v12, v12, v12 row_ror:4 row_mask:0xf bank_mask:0xf bound_ctrl:1
	v_add_f32_dpp v10, v10, v10 row_ror:2 row_mask:0xf bank_mask:0xf bound_ctrl:1
	ds_read_b128 v[84:87], v6 offset:21760
	s_waitcnt lgkmcnt(11)
	v_pk_mul_f32 v[114:115], v[2:3], v[36:37]
	v_add_f32_dpp v12, v12, v12 row_ror:2 row_mask:0xf bank_mask:0xf bound_ctrl:1
	v_add_f32_dpp v10, v10, v10 row_ror:1 row_mask:0xf bank_mask:0xf bound_ctrl:1
	ds_read_b128 v[88:91], v6 offset:22016
	v_pk_mul_f32 v[116:117], v[4:5], v[38:39]
	v_add_f32_dpp v12, v12, v12 row_ror:1 row_mask:0xf bank_mask:0xf bound_ctrl:1
	v_add_f32_e32 v14, v14, v15
	ds_read2_b32 v[112:113], v120 offset0:32 offset1:48
	v_pk_fma_f32 v[114:115], v[40:41], v[64:65], v[114:115] op_sel_hi:[1,0,1]
	v_add_f32_e32 v16, v16, v17
	v_pk_fma_f32 v[116:117], v[42:43], v[64:65], v[116:117] op_sel_hi:[1,0,1]
	ds_read_b128 v[96:99], v6 offset:22528
	v_fmac_f32_e32 v12, v64, v57
	v_fmac_f32_e32 v14, v64, v59
	s_waitcnt lgkmcnt(10)
	v_pk_fma_f32 v[114:115], v[48:49], v[64:65], v[114:115] op_sel:[0,1,0] op_sel_hi:[1,1,1]
	ds_read_b128 v[92:95], v6 offset:22272
	v_fmac_f32_e32 v16, v64, v61
	v_pk_fma_f32 v[116:117], v[50:51], v[64:65], v[116:117] op_sel:[0,1,0] op_sel_hi:[1,1,1]
	v_fma_f32 v14, -v10, v58, v14
	ds_read_b128 v[100:103], v6 offset:22784
	v_fmac_f32_e32 v16, v65, v63
	v_pk_fma_f32 v[114:115], v[44:45], v[10:11], v[114:115] op_sel_hi:[1,0,1] neg_lo:[1,0,0] neg_hi:[1,0,0]
	v_fma_f32 v16, -v10, v60, v16
	ds_read_b128 v[108:111], v7 offset:37312
	v_pk_fma_f32 v[116:117], v[46:47], v[10:11], v[116:117] op_sel_hi:[1,0,1] neg_lo:[1,0,0] neg_hi:[1,0,0]
	v_fma_f32 v16, -v12, v62, v16
	v_pk_fma_f32 v[2:3], v[52:53], v[12:13], v[114:115] op_sel_hi:[1,0,1] neg_lo:[1,0,0] neg_hi:[1,0,0]
	v_pk_fma_f32 v[4:5], v[54:55], v[12:13], v[116:117] op_sel_hi:[1,0,1] neg_lo:[1,0,0] neg_hi:[1,0,0]
	ds_write2st64_b32 v9, v14, v16 offset0:64 offset1:68
	s_waitcnt lgkmcnt(8)
	v_pk_mul_f32 v[10:11], v[4:5], v[70:71]
	ds_read_b128 v[20:23], v6 offset:23040
	v_pk_mul_f32 v[12:13], v[4:5], v[78:79]
	v_pk_fma_f32 v[10:11], v[2:3], v[68:69], v[10:11]
	v_pk_fma_f32 v[12:13], v[2:3], v[76:77], v[12:13]
	ds_read_b128 v[28:31], v6 offset:23552
	v_pk_mul_f32 v[14:15], v[4:5], v[74:75]
	v_add_f32_e32 v10, v10, v11
	v_add_f32_e32 v12, v12, v13
	ds_read_b128 v[24:27], v6 offset:23296
	v_pk_mul_f32 v[16:17], v[4:5], v[82:83]
	v_fma_f32 v12, -v104, v10, v12
	v_add_f32_dpp v10, v10, v10 row_ror:8 row_mask:0xf bank_mask:0xf bound_ctrl:1
	ds_read_b128 v[32:35], v6 offset:23808
	v_pk_fma_f32 v[14:15], v[2:3], v[72:73], v[14:15]
	v_add_f32_dpp v12, v12, v12 row_ror:8 row_mask:0xf bank_mask:0xf bound_ctrl:1
	v_add_f32_dpp v10, v10, v10 row_ror:4 row_mask:0xf bank_mask:0xf bound_ctrl:1
	ds_read_b128 v[56:59], v7 offset:37344
	v_pk_fma_f32 v[16:17], v[2:3], v[80:81], v[16:17]
	v_add_f32_dpp v12, v12, v12 row_ror:4 row_mask:0xf bank_mask:0xf bound_ctrl:1
	v_add_f32_dpp v10, v10, v10 row_ror:2 row_mask:0xf bank_mask:0xf bound_ctrl:1
	ds_read_b128 v[36:39], v6 offset:24064
	s_waitcnt lgkmcnt(11)
	v_pk_mul_f32 v[114:115], v[2:3], v[84:85]
	v_add_f32_dpp v12, v12, v12 row_ror:2 row_mask:0xf bank_mask:0xf bound_ctrl:1
	v_add_f32_dpp v10, v10, v10 row_ror:1 row_mask:0xf bank_mask:0xf bound_ctrl:1
	ds_read_b128 v[40:43], v6 offset:24320
	v_pk_mul_f32 v[116:117], v[4:5], v[86:87]
	v_add_f32_dpp v12, v12, v12 row_ror:1 row_mask:0xf bank_mask:0xf bound_ctrl:1
	v_add_f32_e32 v14, v14, v15
	ds_read2_b32 v[64:65], v120 offset0:64 offset1:80
	v_pk_fma_f32 v[114:115], v[88:89], v[112:113], v[114:115] op_sel_hi:[1,0,1]
	v_add_f32_e32 v16, v16, v17
	v_pk_fma_f32 v[116:117], v[90:91], v[112:113], v[116:117] op_sel_hi:[1,0,1]
	ds_read_b128 v[48:51], v6 offset:24832
	v_fmac_f32_e32 v12, v112, v105
	v_fmac_f32_e32 v14, v112, v107
	s_waitcnt lgkmcnt(10)
	v_pk_fma_f32 v[114:115], v[96:97], v[112:113], v[114:115] op_sel:[0,1,0] op_sel_hi:[1,1,1]
	ds_read_b128 v[44:47], v6 offset:24576
	v_fmac_f32_e32 v16, v112, v109
	v_pk_fma_f32 v[116:117], v[98:99], v[112:113], v[116:117] op_sel:[0,1,0] op_sel_hi:[1,1,1]
	v_fma_f32 v14, -v10, v106, v14
	ds_read_b128 v[52:55], v6 offset:25088
	v_fmac_f32_e32 v16, v113, v111
	v_pk_fma_f32 v[114:115], v[92:93], v[10:11], v[114:115] op_sel_hi:[1,0,1] neg_lo:[1,0,0] neg_hi:[1,0,0]
	v_fma_f32 v16, -v10, v108, v16
	ds_read_b128 v[60:63], v7 offset:37360
	v_pk_fma_f32 v[116:117], v[94:95], v[10:11], v[116:117] op_sel_hi:[1,0,1] neg_lo:[1,0,0] neg_hi:[1,0,0]
	v_fma_f32 v16, -v12, v110, v16
	v_pk_fma_f32 v[2:3], v[100:101], v[12:13], v[114:115] op_sel_hi:[1,0,1] neg_lo:[1,0,0] neg_hi:[1,0,0]
	v_pk_fma_f32 v[4:5], v[102:103], v[12:13], v[116:117] op_sel_hi:[1,0,1] neg_lo:[1,0,0] neg_hi:[1,0,0]
	ds_write2st64_b32 v9, v14, v16 offset0:72 offset1:76
	s_waitcnt lgkmcnt(8)
	v_pk_mul_f32 v[10:11], v[4:5], v[22:23]
	ds_read_b128 v[68:71], v6 offset:25344
	v_pk_mul_f32 v[12:13], v[4:5], v[30:31]
	v_pk_fma_f32 v[10:11], v[2:3], v[20:21], v[10:11]
	v_pk_fma_f32 v[12:13], v[2:3], v[28:29], v[12:13]
	ds_read_b128 v[76:79], v6 offset:25856
	v_pk_mul_f32 v[14:15], v[4:5], v[26:27]
	v_add_f32_e32 v10, v10, v11
	v_add_f32_e32 v12, v12, v13
	ds_read_b128 v[72:75], v6 offset:25600
	v_pk_mul_f32 v[16:17], v[4:5], v[34:35]
	v_fma_f32 v12, -v56, v10, v12
	v_add_f32_dpp v10, v10, v10 row_ror:8 row_mask:0xf bank_mask:0xf bound_ctrl:1
	ds_read_b128 v[80:83], v6 offset:26112
	v_pk_fma_f32 v[14:15], v[2:3], v[24:25], v[14:15]
	v_add_f32_dpp v12, v12, v12 row_ror:8 row_mask:0xf bank_mask:0xf bound_ctrl:1
	v_add_f32_dpp v10, v10, v10 row_ror:4 row_mask:0xf bank_mask:0xf bound_ctrl:1
	ds_read_b128 v[104:107], v7 offset:37392
	v_pk_fma_f32 v[16:17], v[2:3], v[32:33], v[16:17]
	v_add_f32_dpp v12, v12, v12 row_ror:4 row_mask:0xf bank_mask:0xf bound_ctrl:1
	v_add_f32_dpp v10, v10, v10 row_ror:2 row_mask:0xf bank_mask:0xf bound_ctrl:1
	ds_read_b128 v[84:87], v6 offset:26368
	s_waitcnt lgkmcnt(11)
	v_pk_mul_f32 v[114:115], v[2:3], v[36:37]
	v_add_f32_dpp v12, v12, v12 row_ror:2 row_mask:0xf bank_mask:0xf bound_ctrl:1
	v_add_f32_dpp v10, v10, v10 row_ror:1 row_mask:0xf bank_mask:0xf bound_ctrl:1
	ds_read_b128 v[88:91], v6 offset:26624
	v_pk_mul_f32 v[116:117], v[4:5], v[38:39]
	v_add_f32_dpp v12, v12, v12 row_ror:1 row_mask:0xf bank_mask:0xf bound_ctrl:1
	v_add_f32_e32 v14, v14, v15
	ds_read2_b32 v[112:113], v120 offset0:96 offset1:112
	v_pk_fma_f32 v[114:115], v[40:41], v[64:65], v[114:115] op_sel_hi:[1,0,1]
	v_add_f32_e32 v16, v16, v17
	v_pk_fma_f32 v[116:117], v[42:43], v[64:65], v[116:117] op_sel_hi:[1,0,1]
	ds_read_b128 v[96:99], v6 offset:27136
	v_fmac_f32_e32 v12, v64, v57
	v_fmac_f32_e32 v14, v64, v59
	s_waitcnt lgkmcnt(10)
	v_pk_fma_f32 v[114:115], v[48:49], v[64:65], v[114:115] op_sel:[0,1,0] op_sel_hi:[1,1,1]
	ds_read_b128 v[92:95], v6 offset:26880
	v_fmac_f32_e32 v16, v64, v61
	v_pk_fma_f32 v[116:117], v[50:51], v[64:65], v[116:117] op_sel:[0,1,0] op_sel_hi:[1,1,1]
	v_fma_f32 v14, -v10, v58, v14
	ds_read_b128 v[100:103], v6 offset:27392
	v_fmac_f32_e32 v16, v65, v63
	v_pk_fma_f32 v[114:115], v[44:45], v[10:11], v[114:115] op_sel_hi:[1,0,1] neg_lo:[1,0,0] neg_hi:[1,0,0]
	v_fma_f32 v16, -v10, v60, v16
	ds_read_b128 v[108:111], v7 offset:37408
	v_pk_fma_f32 v[116:117], v[46:47], v[10:11], v[116:117] op_sel_hi:[1,0,1] neg_lo:[1,0,0] neg_hi:[1,0,0]
	v_fma_f32 v16, -v12, v62, v16
	v_pk_fma_f32 v[2:3], v[52:53], v[12:13], v[114:115] op_sel_hi:[1,0,1] neg_lo:[1,0,0] neg_hi:[1,0,0]
	v_pk_fma_f32 v[4:5], v[54:55], v[12:13], v[116:117] op_sel_hi:[1,0,1] neg_lo:[1,0,0] neg_hi:[1,0,0]
	ds_write2st64_b32 v9, v14, v16 offset0:80 offset1:84
	s_waitcnt lgkmcnt(8)
	v_pk_mul_f32 v[10:11], v[4:5], v[70:71]
	ds_read_b128 v[20:23], v6 offset:27648
	v_pk_mul_f32 v[12:13], v[4:5], v[78:79]
	v_pk_fma_f32 v[10:11], v[2:3], v[68:69], v[10:11]
	v_pk_fma_f32 v[12:13], v[2:3], v[76:77], v[12:13]
	ds_read_b128 v[28:31], v6 offset:28160
	v_pk_mul_f32 v[14:15], v[4:5], v[74:75]
	v_add_f32_e32 v10, v10, v11
	v_add_f32_e32 v12, v12, v13
	ds_read_b128 v[24:27], v6 offset:27904
	v_pk_mul_f32 v[16:17], v[4:5], v[82:83]
	v_fma_f32 v12, -v104, v10, v12
	v_add_f32_dpp v10, v10, v10 row_ror:8 row_mask:0xf bank_mask:0xf bound_ctrl:1
	ds_read_b128 v[32:35], v6 offset:28416
	v_pk_fma_f32 v[14:15], v[2:3], v[72:73], v[14:15]
	v_add_f32_dpp v12, v12, v12 row_ror:8 row_mask:0xf bank_mask:0xf bound_ctrl:1
	v_add_f32_dpp v10, v10, v10 row_ror:4 row_mask:0xf bank_mask:0xf bound_ctrl:1
	ds_read_b128 v[56:59], v7 offset:37440
	v_pk_fma_f32 v[16:17], v[2:3], v[80:81], v[16:17]
	v_add_f32_dpp v12, v12, v12 row_ror:4 row_mask:0xf bank_mask:0xf bound_ctrl:1
	v_add_f32_dpp v10, v10, v10 row_ror:2 row_mask:0xf bank_mask:0xf bound_ctrl:1
	ds_read_b128 v[36:39], v6 offset:28672
	s_waitcnt lgkmcnt(11)
	v_pk_mul_f32 v[114:115], v[2:3], v[84:85]
	v_add_f32_dpp v12, v12, v12 row_ror:2 row_mask:0xf bank_mask:0xf bound_ctrl:1
	v_add_f32_dpp v10, v10, v10 row_ror:1 row_mask:0xf bank_mask:0xf bound_ctrl:1
	ds_read_b128 v[40:43], v6 offset:28928
	v_pk_mul_f32 v[116:117], v[4:5], v[86:87]
	v_add_f32_dpp v12, v12, v12 row_ror:1 row_mask:0xf bank_mask:0xf bound_ctrl:1
	v_add_f32_e32 v14, v14, v15
	ds_read2_b32 v[64:65], v120 offset0:128 offset1:144
	v_pk_fma_f32 v[114:115], v[88:89], v[112:113], v[114:115] op_sel_hi:[1,0,1]
	v_add_f32_e32 v16, v16, v17
	v_pk_fma_f32 v[116:117], v[90:91], v[112:113], v[116:117] op_sel_hi:[1,0,1]
	ds_read_b128 v[48:51], v6 offset:29440
	v_fmac_f32_e32 v12, v112, v105
	v_fmac_f32_e32 v14, v112, v107
	s_waitcnt lgkmcnt(10)
	v_pk_fma_f32 v[114:115], v[96:97], v[112:113], v[114:115] op_sel:[0,1,0] op_sel_hi:[1,1,1]
	ds_read_b128 v[44:47], v6 offset:29184
	v_fmac_f32_e32 v16, v112, v109
	v_pk_fma_f32 v[116:117], v[98:99], v[112:113], v[116:117] op_sel:[0,1,0] op_sel_hi:[1,1,1]
	v_fma_f32 v14, -v10, v106, v14
	ds_read_b128 v[52:55], v6 offset:29696
	v_fmac_f32_e32 v16, v113, v111
	v_pk_fma_f32 v[114:115], v[92:93], v[10:11], v[114:115] op_sel_hi:[1,0,1] neg_lo:[1,0,0] neg_hi:[1,0,0]
	v_fma_f32 v16, -v10, v108, v16
	ds_read_b128 v[60:63], v7 offset:37456
	v_pk_fma_f32 v[116:117], v[94:95], v[10:11], v[116:117] op_sel_hi:[1,0,1] neg_lo:[1,0,0] neg_hi:[1,0,0]
	v_fma_f32 v16, -v12, v110, v16
	v_pk_fma_f32 v[2:3], v[100:101], v[12:13], v[114:115] op_sel_hi:[1,0,1] neg_lo:[1,0,0] neg_hi:[1,0,0]
	v_pk_fma_f32 v[4:5], v[102:103], v[12:13], v[116:117] op_sel_hi:[1,0,1] neg_lo:[1,0,0] neg_hi:[1,0,0]
	ds_write2st64_b32 v9, v14, v16 offset0:88 offset1:92
	s_waitcnt lgkmcnt(8)
	v_pk_mul_f32 v[10:11], v[4:5], v[22:23]
	ds_read_b128 v[68:71], v6 offset:29952
	v_pk_mul_f32 v[12:13], v[4:5], v[30:31]
	v_pk_fma_f32 v[10:11], v[2:3], v[20:21], v[10:11]
	v_pk_fma_f32 v[12:13], v[2:3], v[28:29], v[12:13]
	ds_read_b128 v[76:79], v6 offset:30464
	v_pk_mul_f32 v[14:15], v[4:5], v[26:27]
	v_add_f32_e32 v10, v10, v11
	v_add_f32_e32 v12, v12, v13
	ds_read_b128 v[72:75], v6 offset:30208
	v_pk_mul_f32 v[16:17], v[4:5], v[34:35]
	v_fma_f32 v12, -v56, v10, v12
	v_add_f32_dpp v10, v10, v10 row_ror:8 row_mask:0xf bank_mask:0xf bound_ctrl:1
	ds_read_b128 v[80:83], v6 offset:30720
	v_pk_fma_f32 v[14:15], v[2:3], v[24:25], v[14:15]
	v_add_f32_dpp v12, v12, v12 row_ror:8 row_mask:0xf bank_mask:0xf bound_ctrl:1
	v_add_f32_dpp v10, v10, v10 row_ror:4 row_mask:0xf bank_mask:0xf bound_ctrl:1
	ds_read_b128 v[104:107], v7 offset:37488
	v_pk_fma_f32 v[16:17], v[2:3], v[32:33], v[16:17]
	v_add_f32_dpp v12, v12, v12 row_ror:4 row_mask:0xf bank_mask:0xf bound_ctrl:1
	v_add_f32_dpp v10, v10, v10 row_ror:2 row_mask:0xf bank_mask:0xf bound_ctrl:1
	ds_read_b128 v[84:87], v6 offset:30976
	s_waitcnt lgkmcnt(11)
	v_pk_mul_f32 v[114:115], v[2:3], v[36:37]
	v_add_f32_dpp v12, v12, v12 row_ror:2 row_mask:0xf bank_mask:0xf bound_ctrl:1
	v_add_f32_dpp v10, v10, v10 row_ror:1 row_mask:0xf bank_mask:0xf bound_ctrl:1
	ds_read_b128 v[88:91], v6 offset:31232
	v_pk_mul_f32 v[116:117], v[4:5], v[38:39]
	v_add_f32_dpp v12, v12, v12 row_ror:1 row_mask:0xf bank_mask:0xf bound_ctrl:1
	v_add_f32_e32 v14, v14, v15
	ds_read2_b32 v[112:113], v120 offset0:160 offset1:176
	v_pk_fma_f32 v[114:115], v[40:41], v[64:65], v[114:115] op_sel_hi:[1,0,1]
	v_add_f32_e32 v16, v16, v17
	v_pk_fma_f32 v[116:117], v[42:43], v[64:65], v[116:117] op_sel_hi:[1,0,1]
	ds_read_b128 v[96:99], v6 offset:31744
	v_fmac_f32_e32 v12, v64, v57
	v_fmac_f32_e32 v14, v64, v59
	s_waitcnt lgkmcnt(10)
	v_pk_fma_f32 v[114:115], v[48:49], v[64:65], v[114:115] op_sel:[0,1,0] op_sel_hi:[1,1,1]
	ds_read_b128 v[92:95], v6 offset:31488
	v_fmac_f32_e32 v16, v64, v61
	v_pk_fma_f32 v[116:117], v[50:51], v[64:65], v[116:117] op_sel:[0,1,0] op_sel_hi:[1,1,1]
	v_fma_f32 v14, -v10, v58, v14
	ds_read_b128 v[100:103], v6 offset:32000
	v_fmac_f32_e32 v16, v65, v63
	v_pk_fma_f32 v[114:115], v[44:45], v[10:11], v[114:115] op_sel_hi:[1,0,1] neg_lo:[1,0,0] neg_hi:[1,0,0]
	v_fma_f32 v16, -v10, v60, v16
	ds_read_b128 v[108:111], v7 offset:37504
	v_pk_fma_f32 v[116:117], v[46:47], v[10:11], v[116:117] op_sel_hi:[1,0,1] neg_lo:[1,0,0] neg_hi:[1,0,0]
	v_fma_f32 v16, -v12, v62, v16
	v_pk_fma_f32 v[2:3], v[52:53], v[12:13], v[114:115] op_sel_hi:[1,0,1] neg_lo:[1,0,0] neg_hi:[1,0,0]
	v_pk_fma_f32 v[4:5], v[54:55], v[12:13], v[116:117] op_sel_hi:[1,0,1] neg_lo:[1,0,0] neg_hi:[1,0,0]
	ds_write2st64_b32 v9, v14, v16 offset0:96 offset1:100
	s_waitcnt lgkmcnt(8)
	v_pk_mul_f32 v[10:11], v[4:5], v[70:71]
	ds_read_b128 v[20:23], v6 offset:32256
	v_pk_mul_f32 v[12:13], v[4:5], v[78:79]
	v_pk_fma_f32 v[10:11], v[2:3], v[68:69], v[10:11]
	v_pk_fma_f32 v[12:13], v[2:3], v[76:77], v[12:13]
	ds_read_b128 v[28:31], v6 offset:32768
	v_pk_mul_f32 v[14:15], v[4:5], v[74:75]
	v_add_f32_e32 v10, v10, v11
	v_add_f32_e32 v12, v12, v13
	ds_read_b128 v[24:27], v6 offset:32512
	v_pk_mul_f32 v[16:17], v[4:5], v[82:83]
	v_fma_f32 v12, -v104, v10, v12
	v_add_f32_dpp v10, v10, v10 row_ror:8 row_mask:0xf bank_mask:0xf bound_ctrl:1
	ds_read_b128 v[32:35], v6 offset:33024
	v_pk_fma_f32 v[14:15], v[2:3], v[72:73], v[14:15]
	v_add_f32_dpp v12, v12, v12 row_ror:8 row_mask:0xf bank_mask:0xf bound_ctrl:1
	v_add_f32_dpp v10, v10, v10 row_ror:4 row_mask:0xf bank_mask:0xf bound_ctrl:1
	ds_read_b128 v[56:59], v7 offset:37536
	v_pk_fma_f32 v[16:17], v[2:3], v[80:81], v[16:17]
	v_add_f32_dpp v12, v12, v12 row_ror:4 row_mask:0xf bank_mask:0xf bound_ctrl:1
	v_add_f32_dpp v10, v10, v10 row_ror:2 row_mask:0xf bank_mask:0xf bound_ctrl:1
	ds_read_b128 v[36:39], v6 offset:33280
	s_waitcnt lgkmcnt(11)
	v_pk_mul_f32 v[114:115], v[2:3], v[84:85]
	v_add_f32_dpp v12, v12, v12 row_ror:2 row_mask:0xf bank_mask:0xf bound_ctrl:1
	v_add_f32_dpp v10, v10, v10 row_ror:1 row_mask:0xf bank_mask:0xf bound_ctrl:1
	ds_read_b128 v[40:43], v6 offset:33536
	v_pk_mul_f32 v[116:117], v[4:5], v[86:87]
	v_add_f32_dpp v12, v12, v12 row_ror:1 row_mask:0xf bank_mask:0xf bound_ctrl:1
	v_add_f32_e32 v14, v14, v15
	ds_read2_b32 v[64:65], v120 offset0:192 offset1:208
	v_pk_fma_f32 v[114:115], v[88:89], v[112:113], v[114:115] op_sel_hi:[1,0,1]
	v_add_f32_e32 v16, v16, v17
	v_pk_fma_f32 v[116:117], v[90:91], v[112:113], v[116:117] op_sel_hi:[1,0,1]
	ds_read_b128 v[48:51], v6 offset:34048
	v_fmac_f32_e32 v12, v112, v105
	v_fmac_f32_e32 v14, v112, v107
	s_waitcnt lgkmcnt(10)
	v_pk_fma_f32 v[114:115], v[96:97], v[112:113], v[114:115] op_sel:[0,1,0] op_sel_hi:[1,1,1]
	ds_read_b128 v[44:47], v6 offset:33792
	v_fmac_f32_e32 v16, v112, v109
	v_pk_fma_f32 v[116:117], v[98:99], v[112:113], v[116:117] op_sel:[0,1,0] op_sel_hi:[1,1,1]
	v_fma_f32 v14, -v10, v106, v14
	ds_read_b128 v[52:55], v6 offset:34304
	v_fmac_f32_e32 v16, v113, v111
	v_pk_fma_f32 v[114:115], v[92:93], v[10:11], v[114:115] op_sel_hi:[1,0,1] neg_lo:[1,0,0] neg_hi:[1,0,0]
	v_fma_f32 v16, -v10, v108, v16
	ds_read_b128 v[60:63], v7 offset:37552
	v_pk_fma_f32 v[116:117], v[94:95], v[10:11], v[116:117] op_sel_hi:[1,0,1] neg_lo:[1,0,0] neg_hi:[1,0,0]
	v_fma_f32 v16, -v12, v110, v16
	v_pk_fma_f32 v[2:3], v[100:101], v[12:13], v[114:115] op_sel_hi:[1,0,1] neg_lo:[1,0,0] neg_hi:[1,0,0]
	v_pk_fma_f32 v[4:5], v[102:103], v[12:13], v[116:117] op_sel_hi:[1,0,1] neg_lo:[1,0,0] neg_hi:[1,0,0]
	ds_write2st64_b32 v9, v14, v16 offset0:104 offset1:108
	s_waitcnt lgkmcnt(8)
	v_pk_mul_f32 v[10:11], v[4:5], v[22:23]
	ds_read_b128 v[68:71], v6 offset:34560
	v_pk_mul_f32 v[12:13], v[4:5], v[30:31]
	v_pk_fma_f32 v[10:11], v[2:3], v[20:21], v[10:11]
	v_pk_fma_f32 v[12:13], v[2:3], v[28:29], v[12:13]
	ds_read_b128 v[76:79], v6 offset:35072
	v_pk_mul_f32 v[14:15], v[4:5], v[26:27]
	v_add_f32_e32 v10, v10, v11
	v_add_f32_e32 v12, v12, v13
	ds_read_b128 v[72:75], v6 offset:34816
	v_pk_mul_f32 v[16:17], v[4:5], v[34:35]
	v_fma_f32 v12, -v56, v10, v12
	v_add_f32_dpp v10, v10, v10 row_ror:8 row_mask:0xf bank_mask:0xf bound_ctrl:1
	ds_read_b128 v[80:83], v6 offset:35328
	v_pk_fma_f32 v[14:15], v[2:3], v[24:25], v[14:15]
	v_add_f32_dpp v12, v12, v12 row_ror:8 row_mask:0xf bank_mask:0xf bound_ctrl:1
	v_add_f32_dpp v10, v10, v10 row_ror:4 row_mask:0xf bank_mask:0xf bound_ctrl:1
	ds_read_b128 v[104:107], v7 offset:37584
	v_pk_fma_f32 v[16:17], v[2:3], v[32:33], v[16:17]
	v_add_f32_dpp v12, v12, v12 row_ror:4 row_mask:0xf bank_mask:0xf bound_ctrl:1
	v_add_f32_dpp v10, v10, v10 row_ror:2 row_mask:0xf bank_mask:0xf bound_ctrl:1
	ds_read_b128 v[84:87], v6 offset:35584
	s_waitcnt lgkmcnt(11)
	v_pk_mul_f32 v[114:115], v[2:3], v[36:37]
	v_add_f32_dpp v12, v12, v12 row_ror:2 row_mask:0xf bank_mask:0xf bound_ctrl:1
	v_add_f32_dpp v10, v10, v10 row_ror:1 row_mask:0xf bank_mask:0xf bound_ctrl:1
	ds_read_b128 v[88:91], v6 offset:35840
	v_pk_mul_f32 v[116:117], v[4:5], v[38:39]
	v_add_f32_dpp v12, v12, v12 row_ror:1 row_mask:0xf bank_mask:0xf bound_ctrl:1
	v_add_f32_e32 v14, v14, v15
	ds_read2_b32 v[112:113], v120 offset0:224 offset1:240
	v_pk_fma_f32 v[114:115], v[40:41], v[64:65], v[114:115] op_sel_hi:[1,0,1]
	v_add_f32_e32 v16, v16, v17
	v_pk_fma_f32 v[116:117], v[42:43], v[64:65], v[116:117] op_sel_hi:[1,0,1]
	ds_read_b128 v[96:99], v6 offset:36352
	v_fmac_f32_e32 v12, v64, v57
	v_fmac_f32_e32 v14, v64, v59
	s_waitcnt lgkmcnt(10)
	v_pk_fma_f32 v[114:115], v[48:49], v[64:65], v[114:115] op_sel:[0,1,0] op_sel_hi:[1,1,1]
	ds_read_b128 v[92:95], v6 offset:36096
	v_fmac_f32_e32 v16, v64, v61
	v_pk_fma_f32 v[116:117], v[50:51], v[64:65], v[116:117] op_sel:[0,1,0] op_sel_hi:[1,1,1]
	v_fma_f32 v14, -v10, v58, v14
	ds_read_b128 v[100:103], v6 offset:36608
	v_fmac_f32_e32 v16, v65, v63
	v_pk_fma_f32 v[114:115], v[44:45], v[10:11], v[114:115] op_sel_hi:[1,0,1] neg_lo:[1,0,0] neg_hi:[1,0,0]
	v_fma_f32 v16, -v10, v60, v16
	ds_read_b128 v[108:111], v7 offset:37600
	v_pk_fma_f32 v[116:117], v[46:47], v[10:11], v[116:117] op_sel_hi:[1,0,1] neg_lo:[1,0,0] neg_hi:[1,0,0]
	v_fma_f32 v16, -v12, v62, v16
	v_pk_fma_f32 v[2:3], v[52:53], v[12:13], v[114:115] op_sel_hi:[1,0,1] neg_lo:[1,0,0] neg_hi:[1,0,0]
	v_pk_fma_f32 v[4:5], v[54:55], v[12:13], v[116:117] op_sel_hi:[1,0,1] neg_lo:[1,0,0] neg_hi:[1,0,0]
	ds_write2st64_b32 v9, v14, v16 offset0:112 offset1:116
	s_waitcnt lgkmcnt(8)
	v_pk_mul_f32 v[10:11], v[4:5], v[70:71]
	v_pk_mul_f32 v[12:13], v[4:5], v[78:79]
	v_pk_fma_f32 v[10:11], v[2:3], v[68:69], v[10:11]
	v_pk_fma_f32 v[12:13], v[2:3], v[76:77], v[12:13]
	v_pk_mul_f32 v[14:15], v[4:5], v[74:75]
	v_add_f32_e32 v10, v10, v11
	v_add_f32_e32 v12, v12, v13
	v_pk_mul_f32 v[16:17], v[4:5], v[82:83]
	v_fma_f32 v12, -v104, v10, v12
	v_add_f32_dpp v10, v10, v10 row_ror:8 row_mask:0xf bank_mask:0xf bound_ctrl:1
	v_pk_fma_f32 v[14:15], v[2:3], v[72:73], v[14:15]
	v_add_f32_dpp v12, v12, v12 row_ror:8 row_mask:0xf bank_mask:0xf bound_ctrl:1
	v_add_f32_dpp v10, v10, v10 row_ror:4 row_mask:0xf bank_mask:0xf bound_ctrl:1
	v_pk_fma_f32 v[16:17], v[2:3], v[80:81], v[16:17]
	v_add_f32_dpp v12, v12, v12 row_ror:4 row_mask:0xf bank_mask:0xf bound_ctrl:1
	v_add_f32_dpp v10, v10, v10 row_ror:2 row_mask:0xf bank_mask:0xf bound_ctrl:1
	s_waitcnt lgkmcnt(5)
	v_pk_mul_f32 v[114:115], v[2:3], v[84:85]
	v_add_f32_dpp v12, v12, v12 row_ror:2 row_mask:0xf bank_mask:0xf bound_ctrl:1
	v_add_f32_dpp v10, v10, v10 row_ror:1 row_mask:0xf bank_mask:0xf bound_ctrl:1
	v_pk_mul_f32 v[116:117], v[4:5], v[86:87]
	v_add_f32_dpp v12, v12, v12 row_ror:1 row_mask:0xf bank_mask:0xf bound_ctrl:1
	v_add_f32_e32 v14, v14, v15
	v_pk_fma_f32 v[114:115], v[88:89], v[112:113], v[114:115] op_sel_hi:[1,0,1]
	v_add_f32_e32 v16, v16, v17
	v_pk_fma_f32 v[116:117], v[90:91], v[112:113], v[116:117] op_sel_hi:[1,0,1]
	v_fmac_f32_e32 v12, v112, v105
	v_fmac_f32_e32 v14, v112, v107
	s_waitcnt lgkmcnt(1)
	v_pk_fma_f32 v[114:115], v[96:97], v[112:113], v[114:115] op_sel:[0,1,0] op_sel_hi:[1,1,1]
	v_fmac_f32_e32 v16, v112, v109
	v_pk_fma_f32 v[116:117], v[98:99], v[112:113], v[116:117] op_sel:[0,1,0] op_sel_hi:[1,1,1]
	v_fma_f32 v14, -v10, v106, v14
	v_fmac_f32_e32 v16, v113, v111
	v_pk_fma_f32 v[114:115], v[92:93], v[10:11], v[114:115] op_sel_hi:[1,0,1] neg_lo:[1,0,0] neg_hi:[1,0,0]
	v_fma_f32 v16, -v10, v108, v16
	v_pk_fma_f32 v[116:117], v[94:95], v[10:11], v[116:117] op_sel_hi:[1,0,1] neg_lo:[1,0,0] neg_hi:[1,0,0]
	v_fma_f32 v16, -v12, v110, v16
	v_pk_fma_f32 v[2:3], v[100:101], v[12:13], v[114:115] op_sel_hi:[1,0,1] neg_lo:[1,0,0] neg_hi:[1,0,0]
	v_pk_fma_f32 v[4:5], v[102:103], v[12:13], v[116:117] op_sel_hi:[1,0,1] neg_lo:[1,0,0] neg_hi:[1,0,0]
	ds_write2st64_b32 v9, v14, v16 offset0:120 offset1:124
	v_add_u32_e32 v6, s1, v6
	v_add_u32_e32 v7, s1, v7
	v_add_u32_e32 v8, s1, v8
	v_add_u32_e32 v9, s1, v9
	v_add_u32_e32 v120, s1, v120
	s_sub_i32 s1, 0, s1
	s_add_i32 s0, s0, 1
	s_cmpk_eq_i32 s0, 0x200
	s_waitcnt lgkmcnt(0)
	s_barrier
	s_cbranch_scc0 .LBB0_652
	s_mov_b64 s[0:1], 0

.LBB0_663:
	s_or_b64 exec, exec, s[20:21]
	s_add_u32 s20, s78, 0xf000000
	s_addc_u32 s21, s79, 0
	s_add_u32 s7, s20, s6
	s_addc_u32 s9, s21, 0
	s_add_u32 s22, s7, s8
	s_addc_u32 s23, s9, 0
	v_mov_b32_e32 v3, 0
	s_waitcnt vmcnt(11)
	v_cvt_f32_f16_sdwa v35, v61 dst_sel:DWORD dst_unused:UNUSED_PAD src0_sel:WORD_1
	v_cvt_f32_f16_e32 v34, v61
	v_lshl_add_u64 v[32:33], s[22:23], 0, v[2:3]
	s_mov_b64 s[22:23], 0x20000
	v_lshl_add_u64 v[38:39], v[28:29], 0, s[22:23]
	v_or_b32_e32 v28, v38, v55
	v_mov_b32_e32 v29, v39
	v_or_b32_e32 v38, v38, v54
	v_lshlrev_b64 v[30:31], 12, v[30:31]
	ds_write_b64 v1, v[34:35] offset:37632
	v_lshlrev_b64 v[34:35], 1, v[28:29]
	v_lshlrev_b64 v[44:45], 1, v[38:39]
	s_mov_b32 s7, 0x40000
	v_lshl_add_u64 v[52:53], v[32:33], 0, v[30:31]
	v_lshl_add_u64 v[28:29], s[70:71], 0, v[34:35]
	v_lshl_add_u64 v[30:31], s[12:13], 0, v[34:35]
	v_lshl_add_u64 v[32:33], s[14:15], 0, v[34:35]
	v_lshl_add_u64 v[36:37], s[16:17], 0, v[34:35]
	v_lshl_add_u64 v[40:41], s[18:19], 0, v[34:35]
	v_lshl_add_u64 v[38:39], s[70:71], 0, v[44:45]
	v_lshl_add_u64 v[42:43], s[12:13], 0, v[44:45]
	v_lshl_add_u64 v[46:47], s[14:15], 0, v[44:45]
	v_add_co_u32_e32 v48, vcc, s7, v56
	global_load_dwordx2 v[28:29], v[28:29], off
	s_nop 0
	global_load_dwordx2 v[30:31], v[30:31], off
	s_nop 0
	global_load_dwordx2 v[32:33], v[32:33], off
	s_nop 0
	global_load_dwordx2 v[34:35], v[36:37], off
	s_nop 0
	global_load_dwordx2 v[36:37], v[40:41], off
	s_nop 0
	global_load_dwordx2 v[40:41], v[38:39], off
	s_nop 0
	global_load_dwordx2 v[38:39], v[42:43], off
	s_nop 0
	global_load_dwordx2 v[42:43], v[46:47], off
	v_lshl_add_u64 v[46:47], s[16:17], 0, v[44:45]
	v_lshl_add_u64 v[44:45], s[18:19], 0, v[44:45]
	v_addc_co_u32_e32 v49, vcc, 0, v57, vcc
	global_load_dwordx2 v[46:47], v[46:47], off
	s_nop 0
	global_load_dwordx2 v[44:45], v[44:45], off
	v_or_b32_e32 v3, v60, v58
	global_load_dword v81, v[48:49], off
	v_lshlrev_b32_e32 v3, 6, v3
	v_add_u32_e32 v3, 0, v3
	v_bfe_u32 v177, v152, 4, 1
	v_sub_u32_e32 v176, 0, v177
	v_lshlrev_b32_e32 v178, 6, v177
	v_sub_u32_e32 v179, 64, v178
	v_bfe_u32 v177, v152, 1, 2
	v_add_u32_e32 v180, 0, v177
	v_and_b32_e32 v180, 3, v180
	v_lshlrev_b32_e32 v180, 4, v180
	v_add3_u32 v160, v3, v178, v180
	v_add3_u32 v164, v3, v179, v180
	v_add_u32_e32 v180, 1, v177
	v_and_b32_e32 v180, 3, v180
	v_lshlrev_b32_e32 v180, 4, v180
	v_add3_u32 v161, v3, v178, v180
	v_add3_u32 v165, v3, v179, v180
	v_add_u32_e32 v180, 2, v177
	v_and_b32_e32 v180, 3, v180
	v_lshlrev_b32_e32 v180, 4, v180
	v_add3_u32 v162, v3, v178, v180
	v_add3_u32 v166, v3, v179, v180
	v_add_u32_e32 v180, 3, v177
	v_and_b32_e32 v180, 3, v180
	v_lshlrev_b32_e32 v180, 4, v180
	v_add3_u32 v163, v3, v178, v180
	v_add3_u32 v167, v3, v179, v180
	v_add_u32_e32 v168, 0x11b00, v160
	v_add_u32_e32 v169, 0x11b00, v161
	v_add_u32_e32 v170, 0x11b00, v162
	v_add_u32_e32 v171, 0x11b00, v163
	v_add_u32_e32 v172, 0x11b00, v164
	v_add_u32_e32 v173, 0x11b00, v165
	v_add_u32_e32 v174, 0x11b00, v166
	v_add_u32_e32 v175, 0x11b00, v167
	ds_read_b128 v[120:123], v160 offset:39680
	ds_read_b128 v[124:127], v161 offset:39680
	ds_read_b128 v[128:131], v162 offset:39680
	ds_read_b128 v[132:135], v163 offset:39680
	ds_read_b128 v[136:139], v164 offset:39680
	ds_read_b128 v[140:143], v165 offset:39680
	ds_read_b128 v[144:147], v166 offset:39680
	ds_read_b128 v[148:151], v167 offset:39680
	s_movk_i32 s7, 0x7fff
	v_mov_b32_e32 v82, 1
	s_mov_b32 s9, 0xffff0000
	s_lshl_b32 s10, s2, 20
	s_and_b32 s10, s10, 0x4000000
	s_waitcnt lgkmcnt(0)
	v_pk_add_f32 v[120:121], v[120:121], v[124:125]
	v_pk_add_f32 v[122:123], v[122:123], v[126:127]
	v_pk_add_f32 v[128:129], v[128:129], v[132:133]
	v_pk_add_f32 v[130:131], v[130:131], v[134:135]
	v_pk_add_f32 v[120:121], v[120:121], v[128:129]
	v_pk_add_f32 v[122:123], v[122:123], v[130:131]
	v_pk_add_f32 v[120:121], v[120:121], v[122:123]
	v_add_f32_e32 v120, v120, v121
	v_pk_add_f32 v[136:137], v[136:137], v[140:141]
	v_pk_add_f32 v[138:139], v[138:139], v[142:143]
	v_pk_add_f32 v[144:145], v[144:145], v[148:149]
	v_pk_add_f32 v[146:147], v[146:147], v[150:151]
	v_pk_add_f32 v[136:137], v[136:137], v[144:145]
	v_pk_add_f32 v[138:139], v[138:139], v[146:147]
	v_pk_add_f32 v[136:137], v[136:137], v[138:139]
	v_add_f32_e32 v136, v136, v137
	v_bfi_b32 v49, v176, v136, v120
	v_bfi_b32 v48, v176, v120, v136
	v_and_b32_sdwa v50, v49, v82 dst_sel:DWORD dst_unused:UNUSED_PAD src0_sel:WORD_1 src1_sel:DWORD
	v_and_b32_sdwa v51, v48, v82 dst_sel:DWORD dst_unused:UNUSED_PAD src0_sel:WORD_1 src1_sel:DWORD
	v_add3_u32 v49, v49, v50, s7
	v_add3_u32 v48, v48, v51, s7
	v_lshrrev_b32_e32 v49, 16, v49
	v_and_or_b32 v48, v48, s9, v49
	global_store_dword v[52:53], v48, off
	v_lshlrev_b64 v[48:49], 12, v[4:5]
	v_lshl_add_u64 v[48:49], s[10:11], 0, v[48:49]
	s_lshl_b32 s10, s25, 5
	v_and_b32_e32 v50, 7, v153
	s_and_b32 s14, s10, 0x780
	v_lshlrev_b32_e32 v52, 2, v50
	v_lshlrev_b64 v[50:51], 11, v[4:5]
	v_or_b32_e32 v48, s14, v48
	s_and_b32 s15, s24, 0x60
	v_or_b32_e32 v50, s14, v50
	v_or3_b32 v48, v48, s15, v52
	v_or3_b32 v50, v50, s15, v52
	v_lshlrev_b64 v[52:53], 11, v[26:27]
	v_lshl_add_u64 v[48:49], s[78:79], 0, v[48:49]
	s_mov_b64 s[12:13], 0xf040000
	s_lshl_b32 s10, s2, 19
	v_lshl_or_b32 v52, v55, 1, v52
	v_lshl_add_u64 v[48:49], v[48:49], 0, s[12:13]
	s_and_b32 s10, s10, 0x2000000
	v_lshl_add_u64 v[50:51], s[70:71], 0, v[50:51]
	v_lshl_add_u64 v[26:27], s[70:71], 0, v[52:53]
	v_lshl_add_u64 v[52:53], s[78:79], 0, v[52:53]
	s_mov_b32 s12, 0x3d800000
	s_mov_b64 s[14:15], 0x40000
	s_mov_b32 s13, s11
	s_barrier
	s_branch .LBB0_665
.LBB0_664:
	ds_read_b128 v[120:123], v160 offset:39680
	ds_read_b128 v[124:127], v161 offset:39680
	ds_read_b128 v[128:131], v162 offset:39680
	ds_read_b128 v[132:135], v163 offset:39680
	ds_read_b128 v[136:139], v164 offset:39680
	ds_read_b128 v[140:143], v165 offset:39680
	ds_read_b128 v[144:147], v166 offset:39680
	ds_read_b128 v[148:151], v167 offset:39680
	v_lshl_add_u64 v[50:51], v[50:51], 0, s[22:23]
	v_lshl_add_u64 v[26:27], v[26:27], 0, s[22:23]
	v_lshl_add_u64 v[52:53], v[52:53], 0, s[22:23]
	s_and_b64 vcc, exec, s[16:17]
	s_nop 0
	s_waitcnt lgkmcnt(0)
	v_pk_add_f32 v[120:121], v[120:121], v[124:125]
	v_pk_add_f32 v[122:123], v[122:123], v[126:127]
	v_pk_add_f32 v[128:129], v[128:129], v[132:133]
	v_pk_add_f32 v[130:131], v[130:131], v[134:135]
	v_pk_add_f32 v[120:121], v[120:121], v[128:129]
	v_pk_add_f32 v[122:123], v[122:123], v[130:131]
	v_pk_add_f32 v[120:121], v[120:121], v[122:123]
	v_add_f32_e32 v120, v120, v121
	v_pk_add_f32 v[136:137], v[136:137], v[140:141]
	v_pk_add_f32 v[138:139], v[138:139], v[142:143]
	v_pk_add_f32 v[144:145], v[144:145], v[148:149]
	v_pk_add_f32 v[146:147], v[146:147], v[150:151]
	v_pk_add_f32 v[136:137], v[136:137], v[144:145]
	v_pk_add_f32 v[138:139], v[138:139], v[146:147]
	v_pk_add_f32 v[136:137], v[136:137], v[138:139]
	v_add_f32_e32 v136, v136, v137
	v_bfi_b32 v55, v176, v136, v120
	v_bfi_b32 v54, v176, v120, v136
	v_and_b32_sdwa v56, v55, v82 dst_sel:DWORD dst_unused:UNUSED_PAD src0_sel:WORD_1 src1_sel:DWORD
	v_and_b32_sdwa v57, v54, v82 dst_sel:DWORD dst_unused:UNUSED_PAD src0_sel:WORD_1 src1_sel:DWORD
	v_add3_u32 v55, v55, v56, s7
	v_add3_u32 v54, v54, v57, s7
	v_lshrrev_b32_e32 v55, 16, v55
	v_and_or_b32 v54, v54, s9, v55
	global_store_dword v[48:49], v54, off
	v_lshl_add_u64 v[48:49], v[48:49], 0, s[14:15]
	s_barrier
	s_cbranch_vccnz .LBB0_675

.LBB0_669:
	ds_read_b128 v[120:123], v168 offset:39680
	ds_read_b128 v[124:127], v169 offset:39680
	ds_read_b128 v[128:131], v170 offset:39680
	ds_read_b128 v[132:135], v171 offset:39680
	ds_read_b128 v[136:139], v172 offset:39680
	ds_read_b128 v[140:143], v173 offset:39680
	ds_read_b128 v[144:147], v174 offset:39680
	ds_read_b128 v[148:151], v175 offset:39680
	s_cmpk_gt_u32 s13, 0x1fd
	s_cselect_b64 s[16:17], -1, 0
	s_nop 0
	s_nop 0
	s_nop 0
	s_waitcnt lgkmcnt(0)
	v_pk_add_f32 v[120:121], v[120:121], v[124:125]
	v_pk_add_f32 v[122:123], v[122:123], v[126:127]
	v_pk_add_f32 v[128:129], v[128:129], v[132:133]
	v_pk_add_f32 v[130:131], v[130:131], v[134:135]
	v_pk_add_f32 v[120:121], v[120:121], v[128:129]
	v_pk_add_f32 v[122:123], v[122:123], v[130:131]
	v_pk_add_f32 v[120:121], v[120:121], v[122:123]
	v_add_f32_e32 v120, v120, v121
	v_pk_add_f32 v[136:137], v[136:137], v[140:141]
	v_pk_add_f32 v[138:139], v[138:139], v[142:143]
	v_pk_add_f32 v[144:145], v[144:145], v[148:149]
	v_pk_add_f32 v[146:147], v[146:147], v[150:151]
	v_pk_add_f32 v[136:137], v[136:137], v[144:145]
	v_pk_add_f32 v[138:139], v[138:139], v[146:147]
	v_pk_add_f32 v[136:137], v[136:137], v[138:139]
	v_add_f32_e32 v136, v136, v137
	v_bfi_b32 v61, v176, v136, v120
	v_bfi_b32 v60, v176, v120, v136
	v_and_b32_sdwa v62, v61, v82 dst_sel:DWORD dst_unused:UNUSED_PAD src0_sel:WORD_1 src1_sel:DWORD
	v_and_b32_sdwa v63, v60, v82 dst_sel:DWORD dst_unused:UNUSED_PAD src0_sel:WORD_1 src1_sel:DWORD
	v_add3_u32 v61, v61, v62, s7
	v_add3_u32 v60, v60, v63, s7
	v_lshrrev_b32_e32 v61, 16, v61
	v_and_or_b32 v62, v60, s9, v61
	v_add_co_u32_e32 v60, vcc, 0xfffe0000, v48
	s_nop 1
	v_addc_co_u32_e32 v61, vcc, -1, v49, vcc
	s_and_b64 vcc, exec, s[16:17]
	global_store_dword v[60:61], v62, off
	s_barrier
	s_cbranch_vccnz .LBB0_673
	s_waitcnt vmcnt(11)
	v_cvt_f32_f16_sdwa v65, v30 dst_sel:DWORD dst_unused:UNUSED_PAD src0_sel:WORD_1
	v_cvt_f32_f16_e32 v64, v30
	s_waitcnt vmcnt(6)
	v_cvt_f32_f16_sdwa v63, v38 dst_sel:DWORD dst_unused:UNUSED_PAD src0_sel:WORD_1
	v_cvt_f32_f16_e32 v62, v38
	v_cvt_f32_f16_sdwa v67, v31 dst_sel:DWORD dst_unused:UNUSED_PAD src0_sel:WORD_1
	v_pk_add_f32 v[84:85], v[64:65], 1.0 op_sel_hi:[1,0] neg_lo:[1,0] neg_hi:[1,0]
	v_cvt_f32_f16_sdwa v65, v39 dst_sel:DWORD dst_unused:UNUSED_PAD src0_sel:WORD_1
	v_cvt_f32_f16_e32 v64, v39
	v_cvt_f32_f16_e32 v66, v31
	v_cvt_f32_f16_sdwa v93, v40 dst_sel:DWORD dst_unused:UNUSED_PAD src0_sel:WORD_1
	v_cvt_f32_f16_e32 v92, v40
	s_waitcnt vmcnt(4)
	v_cvt_f32_f16_sdwa v95, v46 dst_sel:DWORD dst_unused:UNUSED_PAD src0_sel:WORD_1
	v_cvt_f32_f16_e32 v94, v46
	v_cvt_f32_f16_sdwa v103, v47 dst_sel:DWORD dst_unused:UNUSED_PAD src0_sel:WORD_1
	v_cvt_f32_f16_e32 v102, v47
	v_cvt_f32_f16_sdwa v105, v41 dst_sel:DWORD dst_unused:UNUSED_PAD src0_sel:WORD_1
	v_cvt_f32_f16_e32 v104, v41
	v_cvt_f32_f16_sdwa v61, v34 dst_sel:DWORD dst_unused:UNUSED_PAD src0_sel:WORD_1
	v_cvt_f32_f16_e32 v60, v34
	v_pk_add_f32 v[88:89], v[62:63], 1.0 op_sel_hi:[1,0] neg_lo:[1,0] neg_hi:[1,0]
	v_cvt_f32_f16_sdwa v91, v28 dst_sel:DWORD dst_unused:UNUSED_PAD src0_sel:WORD_1
	v_cvt_f32_f16_e32 v90, v28
	v_cvt_f32_f16_sdwa v63, v35 dst_sel:DWORD dst_unused:UNUSED_PAD src0_sel:WORD_1
	v_cvt_f32_f16_e32 v62, v35
	v_cvt_f32_f16_sdwa v101, v29 dst_sel:DWORD dst_unused:UNUSED_PAD src0_sel:WORD_1
	v_cvt_f32_f16_e32 v100, v29
	v_pk_add_f32 v[98:99], v[64:65], 1.0 op_sel_hi:[1,0] neg_lo:[1,0] neg_hi:[1,0]
	v_pk_add_f32 v[86:87], v[66:67], 1.0 op_sel_hi:[1,0] neg_lo:[1,0] neg_hi:[1,0]
	v_pk_mul_f32 v[96:97], v[88:89], v[92:93]
	v_pk_mul_f32 v[68:69], v[84:85], v[94:95]
	v_pk_mul_f32 v[70:71], v[86:87], v[102:103]
	v_pk_mul_f32 v[106:107], v[98:99], v[104:105]
	v_pk_mul_f32 v[64:65], v[84:85], v[90:91]
	v_pk_mul_f32 v[66:67], v[86:87], v[100:101]
	v_pk_mul_f32 v[72:73], v[84:85], v[96:97]
	v_pk_mul_f32 v[74:75], v[86:87], v[106:107]
	v_pk_mul_f32 v[84:85], v[84:85], v[88:89]
	v_pk_mul_f32 v[86:87], v[86:87], v[98:99]
	ds_write_b128 v80, v[60:63]
	ds_write_b128 v80, v[64:67] offset:256
	ds_write_b128 v80, v[68:71] offset:512
	ds_write_b128 v80, v[72:75] offset:768
	ds_write_b128 v80, v[84:87] offset:1024
	v_cvt_f32_f16_e32 v68, v36
	v_cvt_f32_f16_sdwa v70, v36 dst_sel:DWORD dst_unused:UNUSED_PAD src0_sel:WORD_1
	v_cvt_f32_f16_e32 v69, v32
	v_cvt_f32_f16_sdwa v71, v32 dst_sel:DWORD dst_unused:UNUSED_PAD src0_sel:WORD_1
	v_cvt_f32_f16_e32 v75, v33
	v_cvt_f32_f16_sdwa v85, v33 dst_sel:DWORD dst_unused:UNUSED_PAD src0_sel:WORD_1
	v_cvt_f32_f16_e32 v74, v37
	v_cvt_f32_f16_sdwa v84, v37 dst_sel:DWORD dst_unused:UNUSED_PAD src0_sel:WORD_1
	v_mov_b32_e32 v62, v68
	v_mov_b32_e32 v63, v70
	v_mov_b32_e32 v60, v69
	v_mov_b32_e32 v61, v71
	v_pk_mul_f32 v[64:65], v[88:89], v[62:63]
	v_mov_b32_e32 v62, v75
	v_mov_b32_e32 v63, v85
	v_pk_mul_f32 v[60:61], v[88:89], v[60:61]
	v_pk_mul_f32 v[62:63], v[98:99], v[62:63]
	v_mov_b32_e32 v66, v74
	v_mov_b32_e32 v67, v84
	v_mov_b32_e32 v72, v95
	v_pk_mul_f32 v[66:67], v[98:99], v[66:67]
	ds_write_b128 v80, v[60:63] offset:1280
	ds_write_b128 v80, v[64:67] offset:1536
	v_pk_fma_f32 v[60:61], v[94:95], v[68:69], 0 op_sel_hi:[0,1,0]
	v_pk_fma_f32 v[60:61], v[72:73], v[70:71], v[60:61] op_sel_hi:[0,1,1]
	v_mov_b32_e32 v64, v91
	v_pk_fma_f32 v[72:73], v[90:91], v[68:69], 0 op_sel_hi:[0,1,0]
	v_pk_fma_f32 v[68:69], v[96:97], v[68:69], 0 op_sel_hi:[0,1,0]
	v_pk_fma_f32 v[64:65], v[64:65], v[70:71], v[72:73] op_sel_hi:[0,1,1]
	v_pk_fma_f32 v[68:69], v[96:97], v[70:71], v[68:69] op_sel:[1,0,0]
	v_mov_b32_e32 v86, v103
	v_pk_fma_f32 v[60:61], v[102:103], v[74:75], v[60:61] op_sel_hi:[0,1,1]
	v_mov_b32_e32 v66, v101
	v_pk_fma_f32 v[64:65], v[100:101], v[74:75], v[64:65] op_sel_hi:[0,1,1]
	v_pk_fma_f32 v[68:69], v[106:107], v[74:75], v[68:69] op_sel_hi:[0,1,1]
	v_pk_fma_f32 v[60:61], v[86:87], v[84:85], v[60:61] op_sel_hi:[0,1,1]
	v_pk_fma_f32 v[64:65], v[66:67], v[84:85], v[64:65] op_sel_hi:[0,1,1]
	v_pk_fma_f32 v[68:69], v[106:107], v[84:85], v[68:69] op_sel:[1,0,0]
	v_cvt_f32_f16_e32 v85, v42
	v_cvt_f32_f16_sdwa v87, v42 dst_sel:DWORD dst_unused:UNUSED_PAD src0_sel:WORD_1
	v_cvt_f32_f16_e32 v91, v43
	v_cvt_f32_f16_sdwa v95, v43 dst_sel:DWORD dst_unused:UNUSED_PAD src0_sel:WORD_1
	s_waitcnt vmcnt(3)
	v_cvt_f32_f16_e32 v84, v44
	v_cvt_f32_f16_sdwa v86, v44 dst_sel:DWORD dst_unused:UNUSED_PAD src0_sel:WORD_1
	v_cvt_f32_f16_e32 v90, v45
	v_cvt_f32_f16_sdwa v94, v45 dst_sel:DWORD dst_unused:UNUSED_PAD src0_sel:WORD_1
	v_mov_b32_e32 v72, v85
	v_mov_b32_e32 v73, v87
	v_mov_b32_e32 v74, v91
	v_mov_b32_e32 v75, v95
	ds_write_b128 v80, v[72:75] offset:1792
	v_mov_b32_e32 v72, v84
	v_mov_b32_e32 v73, v86
	v_mov_b32_e32 v74, v90
	v_mov_b32_e32 v75, v94
	v_mov_b32_e32 v88, v93
	ds_write_b128 v80, v[72:75] offset:2048
	v_pk_fma_f32 v[72:73], v[92:93], v[84:85], 0 op_sel_hi:[0,1,0]
	v_pk_fma_f32 v[72:73], v[88:89], v[86:87], v[72:73] op_sel_hi:[0,1,1]
	v_mov_b32_e32 v96, v105
	v_pk_fma_f32 v[72:73], v[104:105], v[90:91], v[72:73] op_sel_hi:[0,1,1]
	v_pk_fma_f32 v[72:73], v[96:97], v[94:95], v[72:73] op_sel_hi:[0,1,1]
	v_mov_b32_dpp v62, v60 row_ror:8 row_mask:0xf bank_mask:0xf bound_ctrl:1
	v_mov_b32_dpp v63, v61 row_ror:8 row_mask:0xf bank_mask:0xf bound_ctrl:1
	v_mov_b32_dpp v66, v64 row_ror:8 row_mask:0xf bank_mask:0xf bound_ctrl:1
	v_mov_b32_dpp v67, v65 row_ror:8 row_mask:0xf bank_mask:0xf bound_ctrl:1
	v_mov_b32_dpp v70, v68 row_ror:8 row_mask:0xf bank_mask:0xf bound_ctrl:1
	v_mov_b32_dpp v71, v69 row_ror:8 row_mask:0xf bank_mask:0xf bound_ctrl:1
	v_mov_b32_dpp v74, v72 row_ror:8 row_mask:0xf bank_mask:0xf bound_ctrl:1
	v_mov_b32_dpp v75, v73 row_ror:8 row_mask:0xf bank_mask:0xf bound_ctrl:1
	v_pk_add_f32 v[60:61], v[60:61], v[62:63]
	v_pk_add_f32 v[64:65], v[64:65], v[66:67]
	v_pk_add_f32 v[68:69], v[68:69], v[70:71]
	v_pk_add_f32 v[72:73], v[72:73], v[74:75]
	v_mov_b32_dpp v62, v60 row_ror:4 row_mask:0xf bank_mask:0xf bound_ctrl:1
	v_mov_b32_dpp v63, v61 row_ror:4 row_mask:0xf bank_mask:0xf bound_ctrl:1
	v_mov_b32_dpp v66, v64 row_ror:4 row_mask:0xf bank_mask:0xf bound_ctrl:1
	v_mov_b32_dpp v67, v65 row_ror:4 row_mask:0xf bank_mask:0xf bound_ctrl:1
	v_mov_b32_dpp v70, v68 row_ror:4 row_mask:0xf bank_mask:0xf bound_ctrl:1
	v_mov_b32_dpp v71, v69 row_ror:4 row_mask:0xf bank_mask:0xf bound_ctrl:1
	v_mov_b32_dpp v74, v72 row_ror:4 row_mask:0xf bank_mask:0xf bound_ctrl:1
	v_mov_b32_dpp v75, v73 row_ror:4 row_mask:0xf bank_mask:0xf bound_ctrl:1
	v_pk_add_f32 v[60:61], v[60:61], v[62:63]
	v_pk_add_f32 v[64:65], v[64:65], v[66:67]
	v_pk_add_f32 v[68:69], v[68:69], v[70:71]
	v_pk_add_f32 v[72:73], v[72:73], v[74:75]
	v_mov_b32_dpp v62, v60 row_ror:2 row_mask:0xf bank_mask:0xf bound_ctrl:1
	v_mov_b32_dpp v63, v61 row_ror:2 row_mask:0xf bank_mask:0xf bound_ctrl:1
	v_mov_b32_dpp v66, v64 row_ror:2 row_mask:0xf bank_mask:0xf bound_ctrl:1
	v_mov_b32_dpp v67, v65 row_ror:2 row_mask:0xf bank_mask:0xf bound_ctrl:1
	v_mov_b32_dpp v70, v68 row_ror:2 row_mask:0xf bank_mask:0xf bound_ctrl:1
	v_mov_b32_dpp v71, v69 row_ror:2 row_mask:0xf bank_mask:0xf bound_ctrl:1
	v_mov_b32_dpp v74, v72 row_ror:2 row_mask:0xf bank_mask:0xf bound_ctrl:1
	v_mov_b32_dpp v75, v73 row_ror:2 row_mask:0xf bank_mask:0xf bound_ctrl:1
	v_pk_add_f32 v[60:61], v[60:61], v[62:63]
	v_pk_add_f32 v[64:65], v[64:65], v[66:67]
	v_pk_add_f32 v[68:69], v[68:69], v[70:71]
	v_pk_add_f32 v[72:73], v[72:73], v[74:75]
	v_mov_b32_dpp v62, v60 row_ror:1 row_mask:0xf bank_mask:0xf bound_ctrl:1
	v_mov_b32_dpp v63, v61 row_ror:1 row_mask:0xf bank_mask:0xf bound_ctrl:1
	v_mov_b32_dpp v66, v64 row_ror:1 row_mask:0xf bank_mask:0xf bound_ctrl:1
	v_mov_b32_dpp v67, v65 row_ror:1 row_mask:0xf bank_mask:0xf bound_ctrl:1
	v_mov_b32_dpp v70, v68 row_ror:1 row_mask:0xf bank_mask:0xf bound_ctrl:1
	v_mov_b32_dpp v71, v69 row_ror:1 row_mask:0xf bank_mask:0xf bound_ctrl:1
	v_mov_b32_dpp v74, v72 row_ror:1 row_mask:0xf bank_mask:0xf bound_ctrl:1
	v_mov_b32_dpp v75, v73 row_ror:1 row_mask:0xf bank_mask:0xf bound_ctrl:1
	s_and_saveexec_b64 s[18:19], s[0:1]
	s_cbranch_execz .LBB0_672
	v_pk_add_f32 v[60:61], v[60:61], v[62:63]
	v_pk_add_f32 v[62:63], v[64:65], v[66:67]
	s_nop 0
	v_pk_mul_f32 v[62:63], v[62:63], s[12:13] op_sel_hi:[1,0]
	ds_write_b128 v77, v[60:63] offset:36864
	v_pk_add_f32 v[60:61], v[68:69], v[70:71]
	v_pk_add_f32 v[62:63], v[72:73], v[74:75]
	v_pk_mul_f32 v[60:61], v[60:61], s[12:13] op_sel_hi:[1,0]
	v_pk_mul_f32 v[62:63], v[62:63], s[12:13] op_sel_hi:[1,0]
	ds_write_b128 v77, v[60:63] offset:36880

.LBB0_675:
	ds_read_b128 v[120:123], v168 offset:39680
	ds_read_b128 v[124:127], v169 offset:39680
	ds_read_b128 v[128:131], v170 offset:39680
	ds_read_b128 v[132:135], v171 offset:39680
	ds_read_b128 v[136:139], v172 offset:39680
	ds_read_b128 v[140:143], v173 offset:39680
	ds_read_b128 v[144:147], v174 offset:39680
	ds_read_b128 v[148:151], v175 offset:39680
	s_waitcnt vmcnt(11)
	s_waitcnt vmcnt(6)
	s_waitcnt vmcnt(5)
	s_waitcnt vmcnt(3)
	v_mov_b32_e32 v1, 1
	v_lshl_add_u64 v[4:5], v[4:5], 0, s[4:5]
	s_movk_i32 s0, 0x7fff
	v_lshlrev_b64 v[4:5], 12, v[4:5]
	s_mov_b32 s7, 0
	s_waitcnt lgkmcnt(0)
	v_pk_add_f32 v[120:121], v[120:121], v[124:125]
	v_pk_add_f32 v[122:123], v[122:123], v[126:127]
	v_pk_add_f32 v[128:129], v[128:129], v[132:133]
	v_pk_add_f32 v[130:131], v[130:131], v[134:135]
	v_pk_add_f32 v[120:121], v[120:121], v[128:129]
	v_pk_add_f32 v[122:123], v[122:123], v[130:131]
	v_pk_add_f32 v[120:121], v[120:121], v[122:123]
	v_add_f32_e32 v120, v120, v121
	v_pk_add_f32 v[136:137], v[136:137], v[140:141]
	v_pk_add_f32 v[138:139], v[138:139], v[142:143]
	v_pk_add_f32 v[144:145], v[144:145], v[148:149]
	v_pk_add_f32 v[146:147], v[146:147], v[150:151]
	v_pk_add_f32 v[136:137], v[136:137], v[144:145]
	v_pk_add_f32 v[138:139], v[138:139], v[146:147]
	v_pk_add_f32 v[136:137], v[136:137], v[138:139]
	v_add_f32_e32 v136, v136, v137
	v_bfi_b32 v7, v176, v136, v120
	v_bfi_b32 v6, v176, v120, v136
	v_and_b32_sdwa v3, v7, v1 dst_sel:DWORD dst_unused:UNUSED_PAD src0_sel:WORD_1 src1_sel:DWORD
	v_and_b32_sdwa v1, v6, v1 dst_sel:DWORD dst_unused:UNUSED_PAD src0_sel:WORD_1 src1_sel:DWORD
	v_add3_u32 v3, v7, v3, s0
	v_lshl_add_u64 v[4:5], s[20:21], 0, v[4:5]
	v_add3_u32 v1, v6, v1, s0
	v_lshrrev_b32_e32 v3, 16, v3
	s_mov_b32 s0, 0xffff0000
	v_lshl_add_u64 v[4:5], v[4:5], 0, s[6:7]
	s_mov_b32 s9, s7
	v_and_or_b32 v1, v1, s0, v3
	v_lshl_add_u64 v[4:5], v[4:5], 0, s[8:9]
	v_mov_b32_e32 v3, 0
	v_lshl_add_u64 v[2:3], v[4:5], 0, v[2:3]
	v_add_co_u32_e32 v2, vcc, 0x3fe0000, v2
	s_nop 1
	v_addc_co_u32_e32 v3, vcc, 0, v3, vcc
	global_store_dword v[2:3], v1, off
